# attention-tile in-projection epilogue: one wait after each rope-table load batch; the 131 later vmcnt(0) waits (proved by CFG analysis to guard nothing but store acknowledgements) dropped
# baseline (speedup 1.0000x reference)
.LBB0_309:
	s_waitcnt vmcnt(0)
	s_cmp_lt_u32 s44, 12
	s_cselect_b64 s[4:5], -1, 0
	s_add_i32 s6, s57, 0xfffff200
	s_cmpk_lt_u32 s6, 0x280
	s_cselect_b64 s[6:7], -1, 0
	s_or_b64 s[4:5], s[4:5], s[6:7]
	s_and_b64 s[4:5], s[70:71], s[4:5]
	v_cndmask_b32_e64 v177, 0, 1, s[4:5]
	v_pk_mul_f32 v[128:129], v[128:129], v[216:217] op_sel_hi:[1,0]
	v_pk_mul_f32 v[126:127], v[126:127], v[216:217] op_sel_hi:[1,0]
	v_pk_mul_f32 v[124:125], v[124:125], v[216:217] op_sel_hi:[1,0]
	v_cmp_ne_u32_e64 s[42:43], 1, v177
	s_andn2_b64 vcc, exec, s[4:5]
	v_pk_mul_f32 v[122:123], v[122:123], v[216:217] op_sel_hi:[1,0]
	s_cbranch_vccnz .LBB0_335
	v_and_b32_e32 v193, 64, v226
	v_xor_b32_e32 v177, 16, v226
	v_add_u32_e32 v193, 64, v193
	v_cmp_lt_i32_e32 vcc, v177, v193
	s_nop 1
	v_cndmask_b32_e32 v177, v226, v177, vcc
	v_lshlrev_b32_e32 v177, 2, v177
	ds_bpermute_b32 v221, v177, v126
	ds_bpermute_b32 v219, v177, v122
	v_cmp_lt_i32_e32 vcc, 0, v233
	s_and_saveexec_b64 s[4:5], vcc
	s_xor_b64 s[4:5], exec, s[4:5]
	s_cbranch_execz .LBB0_314
	v_cmp_eq_u32_e32 vcc, 1, v233
	s_and_saveexec_b64 s[6:7], vcc
	s_cbranch_execz .LBB0_313
	v_mov_b32_e32 v238, v126
	s_waitcnt lgkmcnt(0)
	v_mov_b32_e32 v239, v154
	v_mov_b32_e32 v220, v158
	v_pk_mul_f32 v[220:221], v[238:239], v[220:221]
	v_mov_b32_e32 v238, v122
	v_mov_b32_e32 v239, v146
	v_mov_b32_e32 v218, v150
	v_pk_mul_f32 v[218:219], v[238:239], v[218:219]
	v_add_f32_e32 v126, v220, v221
	v_add_f32_e32 v122, v218, v219

.LBB0_314:
	s_andn2_saveexec_b64 s[4:5], s[4:5]
	s_cbranch_execz .LBB0_316
	v_mov_b32_e32 v238, v126
	s_waitcnt lgkmcnt(0)
	v_mov_b32_e32 v239, v154
	v_mov_b32_e32 v220, v158
	v_pk_mul_f32 v[220:221], v[238:239], v[220:221]
	v_mov_b32_e32 v238, v122
	v_mov_b32_e32 v239, v146
	v_mov_b32_e32 v218, v150
	v_pk_mul_f32 v[218:219], v[238:239], v[218:219]
	v_sub_f32_e32 v126, v220, v221
	v_sub_f32_e32 v122, v218, v219
.LBB0_316:
	s_or_b64 exec, exec, s[4:5]
	s_waitcnt lgkmcnt(0)
	ds_bpermute_b32 v221, v177, v127
	ds_bpermute_b32 v219, v177, v123
	v_cmp_lt_i32_e32 vcc, 0, v233
	s_and_saveexec_b64 s[4:5], vcc
	s_xor_b64 s[4:5], exec, s[4:5]
	s_cbranch_execz .LBB0_320
	v_cmp_eq_u32_e32 vcc, 1, v233
	s_and_saveexec_b64 s[6:7], vcc
	s_cbranch_execz .LBB0_319
	v_mov_b32_e32 v238, v159
	v_mov_b32_e32 v239, v155
	v_mov_b32_e32 v220, v127
	v_mul_f32_e32 v218, v159, v127
	s_waitcnt lgkmcnt(0)
	v_pk_fma_f32 v[220:221], v[238:239], v[220:221], v[218:219] op_sel_hi:[1,1,0]
	v_mov_b32_e32 v238, v151
	v_mov_b32_e32 v239, v147
	v_mov_b32_e32 v218, v123
	v_mul_f32_e32 v220, v151, v123
	v_pk_fma_f32 v[218:219], v[238:239], v[218:219], v[220:221] op_sel_hi:[1,1,0]
	v_mov_b32_e32 v127, v221
	v_mov_b32_e32 v123, v219

.LBB0_320:
	s_andn2_saveexec_b64 s[4:5], s[4:5]
	s_cbranch_execz .LBB0_322
	v_mov_b32_e32 v238, v159
	v_mov_b32_e32 v239, v155
	v_mov_b32_e32 v220, v127
	v_mul_f32_e32 v218, v159, v127
	s_waitcnt lgkmcnt(0)
	v_pk_fma_f32 v[220:221], v[238:239], v[220:221], v[218:219] op_sel_hi:[1,1,0] neg_lo:[1,0,0] neg_hi:[1,0,0]
	v_mov_b32_e32 v238, v151
	v_mov_b32_e32 v239, v147
	v_mov_b32_e32 v218, v123
	v_mul_f32_e32 v220, v151, v123
	v_pk_fma_f32 v[218:219], v[238:239], v[218:219], v[220:221] op_sel_hi:[1,1,0] neg_lo:[1,0,0] neg_hi:[1,0,0]
	v_mov_b32_e32 v127, v221
	v_mov_b32_e32 v123, v219
.LBB0_322:
	s_or_b64 exec, exec, s[4:5]
	s_waitcnt lgkmcnt(0)
	ds_bpermute_b32 v221, v177, v128
	ds_bpermute_b32 v219, v177, v124
	v_cmp_lt_i32_e32 vcc, 0, v233
	s_and_saveexec_b64 s[4:5], vcc
	s_xor_b64 s[4:5], exec, s[4:5]
	s_cbranch_execz .LBB0_326
	v_cmp_eq_u32_e32 vcc, 1, v233
	s_and_saveexec_b64 s[6:7], vcc
	s_cbranch_execz .LBB0_325
	v_mov_b32_e32 v238, v160
	v_mov_b32_e32 v239, v156
	v_mov_b32_e32 v220, v128
	s_waitcnt lgkmcnt(1)
	v_mul_f32_e32 v128, v156, v221
	v_pk_fma_f32 v[220:221], v[238:239], v[220:221], v[128:129] op_sel_hi:[1,1,0]
	v_mov_b32_e32 v238, v152
	v_mov_b32_e32 v239, v148
	v_mov_b32_e32 v218, v124
	s_waitcnt lgkmcnt(0)
	v_mul_f32_e32 v124, v148, v219
	v_pk_fma_f32 v[218:219], v[238:239], v[218:219], v[124:125] op_sel_hi:[1,1,0]
	v_mov_b32_e32 v128, v220
	v_mov_b32_e32 v124, v218

.LBB0_326:
	s_andn2_saveexec_b64 s[4:5], s[4:5]
	s_cbranch_execz .LBB0_328
	v_mov_b32_e32 v238, v160
	v_mov_b32_e32 v239, v156
	v_mov_b32_e32 v220, v128
	s_waitcnt lgkmcnt(1)
	v_mul_f32_e32 v128, v156, v221
	v_pk_fma_f32 v[220:221], v[238:239], v[220:221], v[128:129] op_sel_hi:[1,1,0] neg_lo:[0,0,1] neg_hi:[0,0,1]
	v_mov_b32_e32 v238, v152
	v_mov_b32_e32 v239, v148
	v_mov_b32_e32 v218, v124
	s_waitcnt lgkmcnt(0)
	v_mul_f32_e32 v124, v148, v219
	v_pk_fma_f32 v[218:219], v[238:239], v[218:219], v[124:125] op_sel_hi:[1,1,0] neg_lo:[0,0,1] neg_hi:[0,0,1]
	v_mov_b32_e32 v128, v220
	v_mov_b32_e32 v124, v218
.LBB0_328:
	s_or_b64 exec, exec, s[4:5]
	s_waitcnt lgkmcnt(0)
	ds_bpermute_b32 v221, v177, v129
	ds_bpermute_b32 v219, v177, v125
	v_cmp_lt_i32_e32 vcc, 0, v233
	s_and_saveexec_b64 s[4:5], vcc
	s_xor_b64 s[4:5], exec, s[4:5]
	s_cbranch_execz .LBB0_332
	v_cmp_eq_u32_e32 vcc, 1, v233
	s_and_saveexec_b64 s[6:7], vcc
	s_cbranch_execz .LBB0_331
	v_mov_b32_e32 v238, v161
	v_mov_b32_e32 v239, v157
	v_mov_b32_e32 v220, v129
	s_waitcnt lgkmcnt(1)
	v_mul_f32_e32 v218, v157, v221
	s_waitcnt lgkmcnt(0)
	v_pk_fma_f32 v[220:221], v[238:239], v[220:221], v[218:219] op_sel_hi:[1,1,0]
	v_mov_b32_e32 v238, v153
	v_mov_b32_e32 v239, v149
	v_mov_b32_e32 v218, v125
	v_mul_f32_e32 v240, v149, v219
	v_pk_fma_f32 v[218:219], v[238:239], v[218:219], v[240:241] op_sel_hi:[1,1,0]
	v_mov_b32_e32 v129, v220
	v_mov_b32_e32 v125, v218

.LBB0_332:
	s_andn2_saveexec_b64 s[4:5], s[4:5]
	s_cbranch_execz .LBB0_334
	v_mov_b32_e32 v238, v161
	v_mov_b32_e32 v239, v157
	v_mov_b32_e32 v220, v129
	s_waitcnt lgkmcnt(1)
	v_mul_f32_e32 v218, v157, v221
	s_waitcnt lgkmcnt(0)
	v_pk_fma_f32 v[220:221], v[238:239], v[220:221], v[218:219] op_sel_hi:[1,1,0] neg_lo:[0,0,1] neg_hi:[0,0,1]
	v_mov_b32_e32 v238, v153
	v_mov_b32_e32 v239, v149
	v_mov_b32_e32 v218, v125
	v_mul_f32_e32 v240, v149, v219
	v_pk_fma_f32 v[218:219], v[238:239], v[218:219], v[240:241] op_sel_hi:[1,1,0] neg_lo:[0,0,1] neg_hi:[0,0,1]
	v_mov_b32_e32 v129, v220
	v_mov_b32_e32 v125, v218

.LBB0_335:
	s_and_b32 s4, s44, 30
	s_cmp_eq_u32 s4, 14
	s_cselect_b64 s[4:5], -1, 0
	s_cmp_lt_u32 s44, 10
	s_cselect_b64 s[6:7], -1, 0
	s_waitcnt lgkmcnt(0)
	v_pk_mul_f32 v[218:219], v[126:127], s[36:37] op_sel_hi:[1,0]
	v_pk_mul_f32 v[238:239], v[122:123], s[36:37] op_sel_hi:[1,0]
	s_or_b64 s[40:41], s[6:7], s[4:5]
	v_pk_mul_f32 v[220:221], v[128:129], s[36:37] op_sel_hi:[1,0]
	v_pk_mul_f32 v[240:241], v[124:125], s[36:37] op_sel_hi:[1,0]
	v_cndmask_b32_e64 v126, v126, v218, s[40:41]
	v_cndmask_b32_e64 v122, v122, v238, s[40:41]
	v_cndmask_b32_e64 v123, v123, v239, s[40:41]
	v_cndmask_b32_e64 v128, v128, v220, s[40:41]
	v_cndmask_b32_e64 v129, v129, v221, s[40:41]
	v_cndmask_b32_e64 v127, v127, v219, s[40:41]
	v_cndmask_b32_e64 v177, v124, v240, s[40:41]
	v_cndmask_b32_e64 v193, v125, v241, s[40:41]
	v_cvt_pk_bf16_f32 v124, v126, v127
	v_cvt_pk_bf16_f32 v125, v128, v129
	v_cvt_pk_bf16_f32 v126, v122, v123
	v_mov_b64_e32 v[122:123], s[62:63]
	s_movk_i32 s6, 0x1200
	v_mad_i64_i32 v[122:123], s[6:7], v214, s6, v[122:123]
	s_or_b32 s8, s57, 0x80
	v_lshl_add_u64 v[128:129], v[0:1], 1, v[122:123]
	s_movk_i32 s6, 0xf000
	s_cmpk_lt_i32 s8, 0xc00
	v_add_co_u32_e32 v128, vcc, s6, v128
	s_cselect_b64 s[6:7], -1, 0
	s_add_i32 s10, s57, 0xfffff280
	s_cmpk_lt_u32 s10, 0x280
	s_cselect_b64 s[10:11], -1, 0
	v_addc_co_u32_e32 v129, vcc, -1, v129, vcc
	s_or_b64 s[6:7], s[6:7], s[10:11]
	v_cvt_pk_bf16_f32 v127, v177, v193
	flat_store_dwordx4 v[128:129], v[124:127] nt
	s_and_b64 s[6:7], s[70:71], s[6:7]
	v_mov_b32_e32 v217, v216
	v_mov_b32_e32 v124, v216
	v_mov_b32_e32 v125, v216
	v_pk_mul_f32 v[120:121], v[120:121], v[124:125]
	v_pk_mul_f32 v[116:117], v[116:117], v[124:125]
	v_cndmask_b32_e64 v124, 0, 1, s[6:7]
	v_pk_mul_f32 v[118:119], v[118:119], v[216:217]
	v_cmp_ne_u32_e64 s[46:47], 1, v124
	s_andn2_b64 vcc, exec, s[6:7]
	v_pk_mul_f32 v[114:115], v[114:115], v[216:217]
	s_cbranch_vccnz .LBB0_361
	v_and_b32_e32 v125, 64, v226
	v_xor_b32_e32 v124, 16, v226
	v_add_u32_e32 v125, 64, v125
	v_cmp_lt_i32_e32 vcc, v124, v125
	s_nop 1
	v_cndmask_b32_e32 v124, v226, v124, vcc
	v_lshlrev_b32_e32 v128, 2, v124
	ds_bpermute_b32 v127, v128, v118
	ds_bpermute_b32 v125, v128, v114
	v_cmp_lt_i32_e32 vcc, 0, v233
	s_and_saveexec_b64 s[6:7], vcc
	s_xor_b64 s[6:7], exec, s[6:7]
	s_cbranch_execz .LBB0_340
	v_cmp_eq_u32_e32 vcc, 1, v233
	s_and_saveexec_b64 s[44:45], vcc
	s_cbranch_execz .LBB0_339
	v_mov_b32_e32 v214, v118
	v_mov_b32_e32 v215, v154
	v_mov_b32_e32 v126, v158
	s_waitcnt lgkmcnt(0)
	v_pk_mul_f32 v[126:127], v[214:215], v[126:127]
	v_mov_b32_e32 v214, v114
	v_mov_b32_e32 v215, v146
	v_mov_b32_e32 v124, v150
	v_pk_mul_f32 v[124:125], v[214:215], v[124:125]
	v_add_f32_e32 v118, v126, v127
	v_add_f32_e32 v114, v124, v125

.LBB0_340:
	s_andn2_saveexec_b64 s[6:7], s[6:7]
	s_cbranch_execz .LBB0_342
	v_mov_b32_e32 v214, v118
	v_mov_b32_e32 v215, v154
	v_mov_b32_e32 v126, v158
	s_waitcnt lgkmcnt(0)
	v_pk_mul_f32 v[126:127], v[214:215], v[126:127]
	v_mov_b32_e32 v214, v114
	v_mov_b32_e32 v215, v146
	v_mov_b32_e32 v124, v150
	v_pk_mul_f32 v[124:125], v[214:215], v[124:125]
	v_sub_f32_e32 v118, v126, v127
	v_sub_f32_e32 v114, v124, v125
.LBB0_342:
	s_or_b64 exec, exec, s[6:7]
	s_waitcnt lgkmcnt(0)
	ds_bpermute_b32 v127, v128, v119
	ds_bpermute_b32 v125, v128, v115
	v_cmp_lt_i32_e32 vcc, 0, v233
	s_and_saveexec_b64 s[6:7], vcc
	s_xor_b64 s[6:7], exec, s[6:7]
	s_cbranch_execz .LBB0_346
	v_cmp_eq_u32_e32 vcc, 1, v233
	s_and_saveexec_b64 s[44:45], vcc
	s_cbranch_execz .LBB0_345
	v_mov_b32_e32 v214, v159
	v_mov_b32_e32 v215, v155
	v_mov_b32_e32 v126, v119
	v_mul_f32_e32 v124, v159, v119
	s_waitcnt lgkmcnt(0)
	v_pk_fma_f32 v[126:127], v[214:215], v[126:127], v[124:125] op_sel_hi:[1,1,0]
	v_mov_b32_e32 v214, v151
	v_mov_b32_e32 v215, v147
	v_mov_b32_e32 v124, v115
	v_mul_f32_e32 v126, v151, v115
	v_pk_fma_f32 v[124:125], v[214:215], v[124:125], v[126:127] op_sel_hi:[1,1,0]
	v_mov_b32_e32 v119, v127
	v_mov_b32_e32 v115, v125

.LBB0_346:
	s_andn2_saveexec_b64 s[6:7], s[6:7]
	s_cbranch_execz .LBB0_348
	v_mov_b32_e32 v214, v159
	v_mov_b32_e32 v215, v155
	v_mov_b32_e32 v126, v119
	v_mul_f32_e32 v124, v159, v119
	s_waitcnt lgkmcnt(0)
	v_pk_fma_f32 v[126:127], v[214:215], v[126:127], v[124:125] op_sel_hi:[1,1,0] neg_lo:[1,0,0] neg_hi:[1,0,0]
	v_mov_b32_e32 v214, v151
	v_mov_b32_e32 v215, v147
	v_mov_b32_e32 v124, v115
	v_mul_f32_e32 v126, v151, v115
	v_pk_fma_f32 v[124:125], v[214:215], v[124:125], v[126:127] op_sel_hi:[1,1,0] neg_lo:[1,0,0] neg_hi:[1,0,0]
	v_mov_b32_e32 v119, v127
	v_mov_b32_e32 v115, v125
.LBB0_348:
	s_or_b64 exec, exec, s[6:7]
	s_waitcnt lgkmcnt(0)
	ds_bpermute_b32 v127, v128, v120
	ds_bpermute_b32 v125, v128, v116
	v_cmp_lt_i32_e32 vcc, 0, v233
	s_and_saveexec_b64 s[6:7], vcc
	s_xor_b64 s[6:7], exec, s[6:7]
	s_cbranch_execz .LBB0_352
	v_cmp_eq_u32_e32 vcc, 1, v233
	s_and_saveexec_b64 s[44:45], vcc
	s_cbranch_execz .LBB0_351
	v_mov_b32_e32 v214, v160
	v_mov_b32_e32 v215, v156
	v_mov_b32_e32 v126, v120
	s_waitcnt lgkmcnt(1)
	v_mul_f32_e32 v120, v156, v127
	v_pk_fma_f32 v[126:127], v[214:215], v[126:127], v[120:121] op_sel_hi:[1,1,0]
	v_mov_b32_e32 v214, v152
	v_mov_b32_e32 v215, v148
	v_mov_b32_e32 v124, v116
	s_waitcnt lgkmcnt(0)
	v_mul_f32_e32 v116, v148, v125
	v_pk_fma_f32 v[124:125], v[214:215], v[124:125], v[116:117] op_sel_hi:[1,1,0]
	v_mov_b32_e32 v120, v126
	v_mov_b32_e32 v116, v124

.LBB0_352:
	s_andn2_saveexec_b64 s[6:7], s[6:7]
	s_cbranch_execz .LBB0_354
	v_mov_b32_e32 v214, v160
	v_mov_b32_e32 v215, v156
	v_mov_b32_e32 v126, v120
	s_waitcnt lgkmcnt(1)
	v_mul_f32_e32 v120, v156, v127
	v_pk_fma_f32 v[126:127], v[214:215], v[126:127], v[120:121] op_sel_hi:[1,1,0] neg_lo:[0,0,1] neg_hi:[0,0,1]
	v_mov_b32_e32 v214, v152
	v_mov_b32_e32 v215, v148
	v_mov_b32_e32 v124, v116
	s_waitcnt lgkmcnt(0)
	v_mul_f32_e32 v116, v148, v125
	v_pk_fma_f32 v[124:125], v[214:215], v[124:125], v[116:117] op_sel_hi:[1,1,0] neg_lo:[0,0,1] neg_hi:[0,0,1]
	v_mov_b32_e32 v120, v126
	v_mov_b32_e32 v116, v124
.LBB0_354:
	s_or_b64 exec, exec, s[6:7]
	s_waitcnt lgkmcnt(0)
	ds_bpermute_b32 v127, v128, v121
	ds_bpermute_b32 v125, v128, v117
	v_cmp_lt_i32_e32 vcc, 0, v233
	s_and_saveexec_b64 s[6:7], vcc
	s_xor_b64 s[6:7], exec, s[6:7]
	s_cbranch_execz .LBB0_358
	v_cmp_eq_u32_e32 vcc, 1, v233
	s_and_saveexec_b64 s[44:45], vcc
	s_cbranch_execz .LBB0_357
	v_mov_b32_e32 v128, v161
	v_mov_b32_e32 v129, v157
	v_mov_b32_e32 v126, v121
	s_waitcnt lgkmcnt(1)
	v_mul_f32_e32 v124, v157, v127
	s_waitcnt lgkmcnt(0)
	v_pk_fma_f32 v[126:127], v[128:129], v[126:127], v[124:125] op_sel_hi:[1,1,0]
	v_mov_b32_e32 v128, v153
	v_mov_b32_e32 v129, v149
	v_mov_b32_e32 v124, v117
	v_mul_f32_e32 v214, v149, v125
	v_pk_fma_f32 v[124:125], v[128:129], v[124:125], v[214:215] op_sel_hi:[1,1,0]
	v_mov_b32_e32 v121, v126
	v_mov_b32_e32 v117, v124

.LBB0_358:
	s_andn2_saveexec_b64 s[6:7], s[6:7]
	s_cbranch_execz .LBB0_360
	v_mov_b32_e32 v128, v161
	v_mov_b32_e32 v129, v157
	v_mov_b32_e32 v126, v121
	s_waitcnt lgkmcnt(1)
	v_mul_f32_e32 v124, v157, v127
	s_waitcnt lgkmcnt(0)
	v_pk_fma_f32 v[126:127], v[128:129], v[126:127], v[124:125] op_sel_hi:[1,1,0] neg_lo:[0,0,1] neg_hi:[0,0,1]
	v_mov_b32_e32 v128, v153
	v_mov_b32_e32 v129, v149
	v_mov_b32_e32 v124, v117
	v_mul_f32_e32 v214, v149, v125
	v_pk_fma_f32 v[124:125], v[128:129], v[124:125], v[214:215] op_sel_hi:[1,1,0] neg_lo:[0,0,1] neg_hi:[0,0,1]
	v_mov_b32_e32 v121, v126
	v_mov_b32_e32 v117, v124

.LBB0_361:
	s_cmpk_lt_i32 s8, 0xa00
	s_cselect_b64 s[6:7], -1, 0
	s_waitcnt lgkmcnt(0)
	v_pk_mul_f32 v[124:125], v[118:119], s[36:37] op_sel_hi:[1,0]
	v_pk_mul_f32 v[214:215], v[116:117], s[36:37] op_sel_hi:[1,0]
	s_or_b64 s[44:45], s[6:7], s[4:5]
	v_pk_mul_f32 v[128:129], v[114:115], s[36:37] op_sel_hi:[1,0]
	v_cndmask_b32_e64 v118, v118, v124, s[44:45]
	v_cndmask_b32_e64 v119, v119, v125, s[44:45]
	v_cndmask_b32_e64 v124, v116, v214, s[44:45]
	v_cndmask_b32_e64 v117, v117, v215, s[44:45]
	v_add_u32_e32 v214, s57, v236
	v_mov_b32_e32 v215, v1
	v_cndmask_b32_e64 v116, v114, v128, s[44:45]
	v_cvt_pk_bf16_f32 v114, v118, v119
	v_lshl_add_u64 v[118:119], v[214:215], 1, v[122:123]
	s_movk_i32 s4, 0xf100
	v_add_co_u32_e32 v118, vcc, s4, v118
	v_pk_mul_f32 v[126:127], v[120:121], s[36:37] op_sel_hi:[1,0]
	s_nop 0
	v_addc_co_u32_e32 v119, vcc, -1, v119, vcc
	v_pk_mul_f32 v[112:113], v[112:113], v[212:213] op_sel_hi:[1,0]
	v_pk_mul_f32 v[110:111], v[110:111], v[212:213] op_sel_hi:[1,0]
	v_pk_mul_f32 v[108:109], v[108:109], v[212:213] op_sel_hi:[1,0]
	s_and_b64 vcc, exec, s[42:43]
	v_pk_mul_f32 v[106:107], v[106:107], v[212:213] op_sel_hi:[1,0]
	v_cndmask_b32_e64 v120, v120, v126, s[44:45]
	v_cndmask_b32_e64 v121, v121, v127, s[44:45]
	v_cndmask_b32_e64 v125, v115, v129, s[44:45]
	v_cvt_pk_bf16_f32 v115, v120, v121
	v_cvt_pk_bf16_f32 v116, v116, v125
	v_cvt_pk_bf16_f32 v117, v124, v117
	flat_store_dwordx4 v[118:119], v[114:117] nt
	s_cbranch_vccnz .LBB0_387
	s_nop 0
	v_and_b32_e32 v115, 64, v226
	v_xor_b32_e32 v114, 16, v226
	v_add_u32_e32 v115, 64, v115
	v_cmp_lt_i32_e32 vcc, v114, v115
	s_nop 1
	v_cndmask_b32_e32 v114, v226, v114, vcc
	v_lshlrev_b32_e32 v118, 2, v114
	ds_bpermute_b32 v117, v118, v110
	ds_bpermute_b32 v115, v118, v106
	v_cmp_lt_i32_e32 vcc, 0, v233
	s_and_saveexec_b64 s[4:5], vcc
	s_xor_b64 s[4:5], exec, s[4:5]
	s_cbranch_execz .LBB0_366
	v_cmp_eq_u32_e32 vcc, 1, v233
	s_and_saveexec_b64 s[6:7], vcc
	s_cbranch_execz .LBB0_365
	v_mov_b32_e32 v120, v110
	v_mov_b32_e32 v121, v138
	v_mov_b32_e32 v116, v142
	s_waitcnt lgkmcnt(0)
	v_pk_mul_f32 v[116:117], v[120:121], v[116:117]
	v_mov_b32_e32 v120, v106
	v_mov_b32_e32 v121, v130
	v_mov_b32_e32 v114, v134
	v_pk_mul_f32 v[114:115], v[120:121], v[114:115]
	v_add_f32_e32 v110, v116, v117
	v_add_f32_e32 v106, v114, v115

.LBB0_366:
	s_andn2_saveexec_b64 s[4:5], s[4:5]
	s_cbranch_execz .LBB0_368
	v_mov_b32_e32 v120, v110
	v_mov_b32_e32 v121, v138
	v_mov_b32_e32 v116, v142
	s_waitcnt lgkmcnt(0)
	v_pk_mul_f32 v[116:117], v[120:121], v[116:117]
	v_mov_b32_e32 v120, v106
	v_mov_b32_e32 v121, v130
	v_mov_b32_e32 v114, v134
	v_pk_mul_f32 v[114:115], v[120:121], v[114:115]
	v_sub_f32_e32 v110, v116, v117
	v_sub_f32_e32 v106, v114, v115
.LBB0_368:
	s_or_b64 exec, exec, s[4:5]
	s_waitcnt lgkmcnt(0)
	ds_bpermute_b32 v117, v118, v111
	ds_bpermute_b32 v115, v118, v107
	v_cmp_lt_i32_e32 vcc, 0, v233
	s_and_saveexec_b64 s[4:5], vcc
	s_xor_b64 s[4:5], exec, s[4:5]
	s_cbranch_execz .LBB0_372
	v_cmp_eq_u32_e32 vcc, 1, v233
	s_and_saveexec_b64 s[6:7], vcc
	s_cbranch_execz .LBB0_371
	v_mov_b32_e32 v120, v143
	v_mov_b32_e32 v121, v139
	v_mov_b32_e32 v116, v111
	v_mul_f32_e32 v114, v143, v111
	s_waitcnt lgkmcnt(0)
	v_pk_fma_f32 v[116:117], v[120:121], v[116:117], v[114:115] op_sel_hi:[1,1,0]
	v_mov_b32_e32 v120, v135
	v_mov_b32_e32 v121, v131
	v_mov_b32_e32 v114, v107
	v_mul_f32_e32 v116, v135, v107
	v_pk_fma_f32 v[114:115], v[120:121], v[114:115], v[116:117] op_sel_hi:[1,1,0]
	v_mov_b32_e32 v111, v117
	v_mov_b32_e32 v107, v115

.LBB0_372:
	s_andn2_saveexec_b64 s[4:5], s[4:5]
	s_cbranch_execz .LBB0_374
	v_mov_b32_e32 v120, v143
	v_mov_b32_e32 v121, v139
	v_mov_b32_e32 v116, v111
	v_mul_f32_e32 v114, v143, v111
	s_waitcnt lgkmcnt(0)
	v_pk_fma_f32 v[116:117], v[120:121], v[116:117], v[114:115] op_sel_hi:[1,1,0] neg_lo:[1,0,0] neg_hi:[1,0,0]
	v_mov_b32_e32 v120, v135
	v_mov_b32_e32 v121, v131
	v_mov_b32_e32 v114, v107
	v_mul_f32_e32 v116, v135, v107
	v_pk_fma_f32 v[114:115], v[120:121], v[114:115], v[116:117] op_sel_hi:[1,1,0] neg_lo:[1,0,0] neg_hi:[1,0,0]
	v_mov_b32_e32 v111, v117
	v_mov_b32_e32 v107, v115
.LBB0_374:
	s_or_b64 exec, exec, s[4:5]
	s_waitcnt lgkmcnt(0)
	ds_bpermute_b32 v117, v118, v112
	ds_bpermute_b32 v115, v118, v108
	v_cmp_lt_i32_e32 vcc, 0, v233
	s_and_saveexec_b64 s[4:5], vcc
	s_xor_b64 s[4:5], exec, s[4:5]
	s_cbranch_execz .LBB0_378
	v_cmp_eq_u32_e32 vcc, 1, v233
	s_and_saveexec_b64 s[6:7], vcc
	s_cbranch_execz .LBB0_377
	v_mov_b32_e32 v120, v144
	v_mov_b32_e32 v121, v140
	v_mov_b32_e32 v116, v112
	s_waitcnt lgkmcnt(1)
	v_mul_f32_e32 v112, v140, v117
	v_pk_fma_f32 v[116:117], v[120:121], v[116:117], v[112:113] op_sel_hi:[1,1,0]
	v_mov_b32_e32 v120, v136
	v_mov_b32_e32 v121, v132
	v_mov_b32_e32 v114, v108
	s_waitcnt lgkmcnt(0)
	v_mul_f32_e32 v108, v132, v115
	v_pk_fma_f32 v[114:115], v[120:121], v[114:115], v[108:109] op_sel_hi:[1,1,0]
	v_mov_b32_e32 v112, v116
	v_mov_b32_e32 v108, v114

.LBB0_378:
	s_andn2_saveexec_b64 s[4:5], s[4:5]
	s_cbranch_execz .LBB0_380
	v_mov_b32_e32 v120, v144
	v_mov_b32_e32 v121, v140
	v_mov_b32_e32 v116, v112
	s_waitcnt lgkmcnt(1)
	v_mul_f32_e32 v112, v140, v117
	v_pk_fma_f32 v[116:117], v[120:121], v[116:117], v[112:113] op_sel_hi:[1,1,0] neg_lo:[0,0,1] neg_hi:[0,0,1]
	v_mov_b32_e32 v120, v136
	v_mov_b32_e32 v121, v132
	v_mov_b32_e32 v114, v108
	s_waitcnt lgkmcnt(0)
	v_mul_f32_e32 v108, v132, v115
	v_pk_fma_f32 v[114:115], v[120:121], v[114:115], v[108:109] op_sel_hi:[1,1,0] neg_lo:[0,0,1] neg_hi:[0,0,1]
	v_mov_b32_e32 v112, v116
	v_mov_b32_e32 v108, v114
.LBB0_380:
	s_or_b64 exec, exec, s[4:5]
	s_waitcnt lgkmcnt(0)
	ds_bpermute_b32 v117, v118, v113
	ds_bpermute_b32 v115, v118, v109
	v_cmp_lt_i32_e32 vcc, 0, v233
	s_and_saveexec_b64 s[4:5], vcc
	s_xor_b64 s[4:5], exec, s[4:5]
	s_cbranch_execz .LBB0_384
	v_cmp_eq_u32_e32 vcc, 1, v233
	s_and_saveexec_b64 s[6:7], vcc
	s_cbranch_execz .LBB0_383
	v_mov_b32_e32 v118, v145
	v_mov_b32_e32 v119, v141
	v_mov_b32_e32 v116, v113
	s_waitcnt lgkmcnt(1)
	v_mul_f32_e32 v114, v141, v117
	s_waitcnt lgkmcnt(0)
	v_pk_fma_f32 v[116:117], v[118:119], v[116:117], v[114:115] op_sel_hi:[1,1,0]
	v_mov_b32_e32 v118, v137
	v_mov_b32_e32 v119, v133
	v_mov_b32_e32 v114, v109
	v_mul_f32_e32 v120, v133, v115
	v_pk_fma_f32 v[114:115], v[118:119], v[114:115], v[120:121] op_sel_hi:[1,1,0]
	v_mov_b32_e32 v113, v116
	v_mov_b32_e32 v109, v114

.LBB0_384:
	s_andn2_saveexec_b64 s[4:5], s[4:5]
	s_cbranch_execz .LBB0_386
	v_mov_b32_e32 v118, v145
	v_mov_b32_e32 v119, v141
	v_mov_b32_e32 v116, v113
	s_waitcnt lgkmcnt(1)
	v_mul_f32_e32 v114, v141, v117
	s_waitcnt lgkmcnt(0)
	v_pk_fma_f32 v[116:117], v[118:119], v[116:117], v[114:115] op_sel_hi:[1,1,0] neg_lo:[0,0,1] neg_hi:[0,0,1]
	v_mov_b32_e32 v118, v137
	v_mov_b32_e32 v119, v133
	v_mov_b32_e32 v114, v109
	v_mul_f32_e32 v120, v133, v115
	v_pk_fma_f32 v[114:115], v[118:119], v[114:115], v[120:121] op_sel_hi:[1,1,0] neg_lo:[0,0,1] neg_hi:[0,0,1]
	v_mov_b32_e32 v113, v116
	v_mov_b32_e32 v109, v114

.LBB0_387:
	s_waitcnt lgkmcnt(0)
	v_pk_mul_f32 v[114:115], v[110:111], s[36:37] op_sel_hi:[1,0]
	v_pk_mul_f32 v[118:119], v[106:107], s[36:37] op_sel_hi:[1,0]
	v_pk_mul_f32 v[116:117], v[112:113], s[36:37] op_sel_hi:[1,0]
	v_pk_mul_f32 v[120:121], v[108:109], s[36:37] op_sel_hi:[1,0]
	v_cndmask_b32_e64 v110, v110, v114, s[40:41]
	v_cndmask_b32_e64 v106, v106, v118, s[40:41]
	v_cndmask_b32_e64 v107, v107, v119, s[40:41]
	v_cndmask_b32_e64 v112, v112, v116, s[40:41]
	v_cndmask_b32_e64 v113, v113, v117, s[40:41]
	v_cndmask_b32_e64 v111, v111, v115, s[40:41]
	v_cndmask_b32_e64 v114, v108, v120, s[40:41]
	v_cndmask_b32_e64 v115, v109, v121, s[40:41]
	v_cvt_pk_bf16_f32 v108, v110, v111
	v_cvt_pk_bf16_f32 v109, v112, v113
	v_cvt_pk_bf16_f32 v110, v106, v107
	v_mov_b64_e32 v[106:107], s[62:63]
	s_movk_i32 s4, 0x1200
	v_mad_i64_i32 v[106:107], s[4:5], v210, s4, v[106:107]
	v_lshl_add_u64 v[112:113], v[0:1], 1, v[106:107]
	s_movk_i32 s4, 0xf000
	v_add_co_u32_e32 v112, vcc, s4, v112
	v_mov_b32_e32 v213, v212
	s_nop 0
	v_addc_co_u32_e32 v113, vcc, -1, v113, vcc
	v_cvt_pk_bf16_f32 v111, v114, v115
	flat_store_dwordx4 v[112:113], v[108:111] nt
	v_pk_mul_f32 v[102:103], v[102:103], v[212:213]
	s_and_b64 vcc, exec, s[46:47]
	v_mov_b32_e32 v108, v212
	v_mov_b32_e32 v109, v212
	v_pk_mul_f32 v[104:105], v[104:105], v[108:109]
	v_pk_mul_f32 v[100:101], v[100:101], v[108:109]
	v_pk_mul_f32 v[98:99], v[98:99], v[212:213]
	s_cbranch_vccnz .LBB0_413
	v_and_b32_e32 v109, 64, v226
	v_xor_b32_e32 v108, 16, v226
	v_add_u32_e32 v109, 64, v109
	v_cmp_lt_i32_e32 vcc, v108, v109
	s_nop 1
	v_cndmask_b32_e32 v108, v226, v108, vcc
	v_lshlrev_b32_e32 v112, 2, v108
	ds_bpermute_b32 v111, v112, v102
	ds_bpermute_b32 v109, v112, v98
	v_cmp_lt_i32_e32 vcc, 0, v233
	s_and_saveexec_b64 s[4:5], vcc
	s_xor_b64 s[4:5], exec, s[4:5]
	s_cbranch_execz .LBB0_392
	v_cmp_eq_u32_e32 vcc, 1, v233
	s_and_saveexec_b64 s[6:7], vcc
	s_cbranch_execz .LBB0_391
	v_mov_b32_e32 v114, v102
	v_mov_b32_e32 v115, v138
	v_mov_b32_e32 v110, v142
	s_waitcnt lgkmcnt(0)
	v_pk_mul_f32 v[110:111], v[114:115], v[110:111]
	v_mov_b32_e32 v114, v98
	v_mov_b32_e32 v115, v130
	v_mov_b32_e32 v108, v134
	v_pk_mul_f32 v[108:109], v[114:115], v[108:109]
	v_add_f32_e32 v102, v110, v111
	v_add_f32_e32 v98, v108, v109

.LBB0_392:
	s_andn2_saveexec_b64 s[4:5], s[4:5]
	s_cbranch_execz .LBB0_394
	v_mov_b32_e32 v114, v102
	v_mov_b32_e32 v115, v138
	v_mov_b32_e32 v110, v142
	s_waitcnt lgkmcnt(0)
	v_pk_mul_f32 v[110:111], v[114:115], v[110:111]
	v_mov_b32_e32 v114, v98
	v_mov_b32_e32 v115, v130
	v_mov_b32_e32 v108, v134
	v_pk_mul_f32 v[108:109], v[114:115], v[108:109]
	v_sub_f32_e32 v102, v110, v111
	v_sub_f32_e32 v98, v108, v109
.LBB0_394:
	s_or_b64 exec, exec, s[4:5]
	s_waitcnt lgkmcnt(0)
	ds_bpermute_b32 v111, v112, v103
	ds_bpermute_b32 v109, v112, v99
	v_cmp_lt_i32_e32 vcc, 0, v233
	s_and_saveexec_b64 s[4:5], vcc
	s_xor_b64 s[4:5], exec, s[4:5]
	s_cbranch_execz .LBB0_398
	v_cmp_eq_u32_e32 vcc, 1, v233
	s_and_saveexec_b64 s[6:7], vcc
	s_cbranch_execz .LBB0_397
	v_mov_b32_e32 v114, v143
	v_mov_b32_e32 v115, v139
	v_mov_b32_e32 v110, v103
	v_mul_f32_e32 v108, v143, v103
	s_waitcnt lgkmcnt(0)
	v_pk_fma_f32 v[110:111], v[114:115], v[110:111], v[108:109] op_sel_hi:[1,1,0]
	v_mov_b32_e32 v114, v135
	v_mov_b32_e32 v115, v131
	v_mov_b32_e32 v108, v99
	v_mul_f32_e32 v110, v135, v99
	v_pk_fma_f32 v[108:109], v[114:115], v[108:109], v[110:111] op_sel_hi:[1,1,0]
	v_mov_b32_e32 v103, v111
	v_mov_b32_e32 v99, v109

.LBB0_398:
	s_andn2_saveexec_b64 s[4:5], s[4:5]
	s_cbranch_execz .LBB0_400
	v_mov_b32_e32 v114, v143
	v_mov_b32_e32 v115, v139
	v_mov_b32_e32 v110, v103
	v_mul_f32_e32 v108, v143, v103
	s_waitcnt lgkmcnt(0)
	v_pk_fma_f32 v[110:111], v[114:115], v[110:111], v[108:109] op_sel_hi:[1,1,0] neg_lo:[1,0,0] neg_hi:[1,0,0]
	v_mov_b32_e32 v114, v135
	v_mov_b32_e32 v115, v131
	v_mov_b32_e32 v108, v99
	v_mul_f32_e32 v110, v135, v99
	v_pk_fma_f32 v[108:109], v[114:115], v[108:109], v[110:111] op_sel_hi:[1,1,0] neg_lo:[1,0,0] neg_hi:[1,0,0]
	v_mov_b32_e32 v103, v111
	v_mov_b32_e32 v99, v109
.LBB0_400:
	s_or_b64 exec, exec, s[4:5]
	s_waitcnt lgkmcnt(0)
	ds_bpermute_b32 v111, v112, v104
	ds_bpermute_b32 v109, v112, v100
	v_cmp_lt_i32_e32 vcc, 0, v233
	s_and_saveexec_b64 s[4:5], vcc
	s_xor_b64 s[4:5], exec, s[4:5]
	s_cbranch_execz .LBB0_404
	v_cmp_eq_u32_e32 vcc, 1, v233
	s_and_saveexec_b64 s[6:7], vcc
	s_cbranch_execz .LBB0_403
	v_mov_b32_e32 v114, v144
	v_mov_b32_e32 v115, v140
	v_mov_b32_e32 v110, v104
	s_waitcnt lgkmcnt(1)
	v_mul_f32_e32 v104, v140, v111
	v_pk_fma_f32 v[110:111], v[114:115], v[110:111], v[104:105] op_sel_hi:[1,1,0]
	v_mov_b32_e32 v114, v136
	v_mov_b32_e32 v115, v132
	v_mov_b32_e32 v108, v100
	s_waitcnt lgkmcnt(0)
	v_mul_f32_e32 v100, v132, v109
	v_pk_fma_f32 v[108:109], v[114:115], v[108:109], v[100:101] op_sel_hi:[1,1,0]
	v_mov_b32_e32 v104, v110
	v_mov_b32_e32 v100, v108

.LBB0_404:
	s_andn2_saveexec_b64 s[4:5], s[4:5]
	s_cbranch_execz .LBB0_406
	v_mov_b32_e32 v114, v144
	v_mov_b32_e32 v115, v140
	v_mov_b32_e32 v110, v104
	s_waitcnt lgkmcnt(1)
	v_mul_f32_e32 v104, v140, v111
	v_pk_fma_f32 v[110:111], v[114:115], v[110:111], v[104:105] op_sel_hi:[1,1,0] neg_lo:[0,0,1] neg_hi:[0,0,1]
	v_mov_b32_e32 v114, v136
	v_mov_b32_e32 v115, v132
	v_mov_b32_e32 v108, v100
	s_waitcnt lgkmcnt(0)
	v_mul_f32_e32 v100, v132, v109
	v_pk_fma_f32 v[108:109], v[114:115], v[108:109], v[100:101] op_sel_hi:[1,1,0] neg_lo:[0,0,1] neg_hi:[0,0,1]
	v_mov_b32_e32 v104, v110
	v_mov_b32_e32 v100, v108
.LBB0_406:
	s_or_b64 exec, exec, s[4:5]
	s_waitcnt lgkmcnt(0)
	ds_bpermute_b32 v111, v112, v105
	ds_bpermute_b32 v109, v112, v101
	v_cmp_lt_i32_e32 vcc, 0, v233
	s_and_saveexec_b64 s[4:5], vcc
	s_xor_b64 s[4:5], exec, s[4:5]
	s_cbranch_execz .LBB0_410
	v_cmp_eq_u32_e32 vcc, 1, v233
	s_and_saveexec_b64 s[6:7], vcc
	s_cbranch_execz .LBB0_409
	v_mov_b32_e32 v112, v145
	v_mov_b32_e32 v113, v141
	v_mov_b32_e32 v110, v105
	s_waitcnt lgkmcnt(1)
	v_mul_f32_e32 v108, v141, v111
	s_waitcnt lgkmcnt(0)
	v_pk_fma_f32 v[110:111], v[112:113], v[110:111], v[108:109] op_sel_hi:[1,1,0]
	v_mov_b32_e32 v112, v137
	v_mov_b32_e32 v113, v133
	v_mov_b32_e32 v108, v101
	v_mul_f32_e32 v114, v133, v109
	v_pk_fma_f32 v[108:109], v[112:113], v[108:109], v[114:115] op_sel_hi:[1,1,0]
	v_mov_b32_e32 v105, v110
	v_mov_b32_e32 v101, v108

.LBB0_410:
	s_andn2_saveexec_b64 s[4:5], s[4:5]
	s_cbranch_execz .LBB0_412
	v_mov_b32_e32 v112, v145
	v_mov_b32_e32 v113, v141
	v_mov_b32_e32 v110, v105
	s_waitcnt lgkmcnt(1)
	v_mul_f32_e32 v108, v141, v111
	s_waitcnt lgkmcnt(0)
	v_pk_fma_f32 v[110:111], v[112:113], v[110:111], v[108:109] op_sel_hi:[1,1,0] neg_lo:[0,0,1] neg_hi:[0,0,1]
	v_mov_b32_e32 v112, v137
	v_mov_b32_e32 v113, v133
	v_mov_b32_e32 v108, v101
	v_mul_f32_e32 v114, v133, v109
	v_pk_fma_f32 v[108:109], v[112:113], v[108:109], v[114:115] op_sel_hi:[1,1,0] neg_lo:[0,0,1] neg_hi:[0,0,1]
	v_mov_b32_e32 v105, v110
	v_mov_b32_e32 v101, v108

.LBB0_415:
	s_waitcnt vmcnt(0)
	v_pk_mul_f32 v[96:97], v[96:97], v[208:209] op_sel_hi:[1,0]
	v_pk_mul_f32 v[94:95], v[94:95], v[208:209] op_sel_hi:[1,0]
	v_pk_mul_f32 v[92:93], v[92:93], v[208:209] op_sel_hi:[1,0]
	s_and_b64 vcc, exec, s[42:43]
	v_pk_mul_f32 v[90:91], v[90:91], v[208:209] op_sel_hi:[1,0]
	s_cbranch_vccnz .LBB0_441
	v_and_b32_e32 v193, 64, v226
	v_xor_b32_e32 v177, 16, v226
	v_add_u32_e32 v193, 64, v193
	v_cmp_lt_i32_e32 vcc, v177, v193
	s_nop 1
	v_cndmask_b32_e32 v177, v226, v177, vcc
	v_lshlrev_b32_e32 v177, 2, v177
	ds_bpermute_b32 v213, v177, v94
	ds_bpermute_b32 v211, v177, v90
	v_cmp_lt_i32_e32 vcc, 0, v233
	s_and_saveexec_b64 s[4:5], vcc
	s_xor_b64 s[4:5], exec, s[4:5]
	s_cbranch_execz .LBB0_420
	v_cmp_eq_u32_e32 vcc, 1, v233
	s_and_saveexec_b64 s[6:7], vcc
	s_cbranch_execz .LBB0_419
	v_mov_b32_e32 v216, v94
	s_waitcnt lgkmcnt(0)
	v_mov_b32_e32 v217, v122
	v_mov_b32_e32 v212, v126
	v_pk_mul_f32 v[212:213], v[216:217], v[212:213]
	v_mov_b32_e32 v216, v90
	v_mov_b32_e32 v217, v114
	v_mov_b32_e32 v210, v118
	v_pk_mul_f32 v[210:211], v[216:217], v[210:211]
	v_add_f32_e32 v94, v212, v213
	v_add_f32_e32 v90, v210, v211

.LBB0_420:
	s_andn2_saveexec_b64 s[4:5], s[4:5]
	s_cbranch_execz .LBB0_422
	v_mov_b32_e32 v216, v94
	s_waitcnt lgkmcnt(0)
	v_mov_b32_e32 v217, v122
	v_mov_b32_e32 v212, v126
	v_pk_mul_f32 v[212:213], v[216:217], v[212:213]
	v_mov_b32_e32 v216, v90
	v_mov_b32_e32 v217, v114
	v_mov_b32_e32 v210, v118
	v_pk_mul_f32 v[210:211], v[216:217], v[210:211]
	v_sub_f32_e32 v94, v212, v213
	v_sub_f32_e32 v90, v210, v211
.LBB0_422:
	s_or_b64 exec, exec, s[4:5]
	s_waitcnt lgkmcnt(0)
	ds_bpermute_b32 v213, v177, v95
	ds_bpermute_b32 v211, v177, v91
	v_cmp_lt_i32_e32 vcc, 0, v233
	s_and_saveexec_b64 s[4:5], vcc
	s_xor_b64 s[4:5], exec, s[4:5]
	s_cbranch_execz .LBB0_426
	v_cmp_eq_u32_e32 vcc, 1, v233
	s_and_saveexec_b64 s[6:7], vcc
	s_cbranch_execz .LBB0_425
	v_mov_b32_e32 v216, v127
	v_mov_b32_e32 v217, v123
	v_mov_b32_e32 v212, v95
	v_mul_f32_e32 v210, v127, v95
	s_waitcnt lgkmcnt(0)
	v_pk_fma_f32 v[212:213], v[216:217], v[212:213], v[210:211] op_sel_hi:[1,1,0]
	v_mov_b32_e32 v216, v119
	v_mov_b32_e32 v217, v115
	v_mov_b32_e32 v210, v91
	v_mul_f32_e32 v212, v119, v91
	v_pk_fma_f32 v[210:211], v[216:217], v[210:211], v[212:213] op_sel_hi:[1,1,0]
	v_mov_b32_e32 v95, v213
	v_mov_b32_e32 v91, v211

.LBB0_426:
	s_andn2_saveexec_b64 s[4:5], s[4:5]
	s_cbranch_execz .LBB0_428
	v_mov_b32_e32 v216, v127
	v_mov_b32_e32 v217, v123
	v_mov_b32_e32 v212, v95
	v_mul_f32_e32 v210, v127, v95
	s_waitcnt lgkmcnt(0)
	v_pk_fma_f32 v[212:213], v[216:217], v[212:213], v[210:211] op_sel_hi:[1,1,0] neg_lo:[1,0,0] neg_hi:[1,0,0]
	v_mov_b32_e32 v216, v119
	v_mov_b32_e32 v217, v115
	v_mov_b32_e32 v210, v91
	v_mul_f32_e32 v212, v119, v91
	v_pk_fma_f32 v[210:211], v[216:217], v[210:211], v[212:213] op_sel_hi:[1,1,0] neg_lo:[1,0,0] neg_hi:[1,0,0]
	v_mov_b32_e32 v95, v213
	v_mov_b32_e32 v91, v211
.LBB0_428:
	s_or_b64 exec, exec, s[4:5]
	s_waitcnt lgkmcnt(0)
	ds_bpermute_b32 v213, v177, v96
	ds_bpermute_b32 v211, v177, v92
	v_cmp_lt_i32_e32 vcc, 0, v233
	s_and_saveexec_b64 s[4:5], vcc
	s_xor_b64 s[4:5], exec, s[4:5]
	s_cbranch_execz .LBB0_432
	v_cmp_eq_u32_e32 vcc, 1, v233
	s_and_saveexec_b64 s[6:7], vcc
	s_cbranch_execz .LBB0_431
	v_mov_b32_e32 v216, v128
	v_mov_b32_e32 v217, v124
	v_mov_b32_e32 v212, v96
	s_waitcnt lgkmcnt(1)
	v_mul_f32_e32 v96, v124, v213
	v_pk_fma_f32 v[212:213], v[216:217], v[212:213], v[96:97] op_sel_hi:[1,1,0]
	v_mov_b32_e32 v216, v120
	v_mov_b32_e32 v217, v116
	v_mov_b32_e32 v210, v92
	s_waitcnt lgkmcnt(0)
	v_mul_f32_e32 v92, v116, v211
	v_pk_fma_f32 v[210:211], v[216:217], v[210:211], v[92:93] op_sel_hi:[1,1,0]
	v_mov_b32_e32 v96, v212
	v_mov_b32_e32 v92, v210

.LBB0_432:
	s_andn2_saveexec_b64 s[4:5], s[4:5]
	s_cbranch_execz .LBB0_434
	v_mov_b32_e32 v216, v128
	v_mov_b32_e32 v217, v124
	v_mov_b32_e32 v212, v96
	s_waitcnt lgkmcnt(1)
	v_mul_f32_e32 v96, v124, v213
	v_pk_fma_f32 v[212:213], v[216:217], v[212:213], v[96:97] op_sel_hi:[1,1,0] neg_lo:[0,0,1] neg_hi:[0,0,1]
	v_mov_b32_e32 v216, v120
	v_mov_b32_e32 v217, v116
	v_mov_b32_e32 v210, v92
	s_waitcnt lgkmcnt(0)
	v_mul_f32_e32 v92, v116, v211
	v_pk_fma_f32 v[210:211], v[216:217], v[210:211], v[92:93] op_sel_hi:[1,1,0] neg_lo:[0,0,1] neg_hi:[0,0,1]
	v_mov_b32_e32 v96, v212
	v_mov_b32_e32 v92, v210
.LBB0_434:
	s_or_b64 exec, exec, s[4:5]
	s_waitcnt lgkmcnt(0)
	ds_bpermute_b32 v213, v177, v97
	ds_bpermute_b32 v211, v177, v93
	v_cmp_lt_i32_e32 vcc, 0, v233
	s_and_saveexec_b64 s[4:5], vcc
	s_xor_b64 s[4:5], exec, s[4:5]
	s_cbranch_execz .LBB0_438
	v_cmp_eq_u32_e32 vcc, 1, v233
	s_and_saveexec_b64 s[6:7], vcc
	s_cbranch_execz .LBB0_437
	v_mov_b32_e32 v216, v129
	v_mov_b32_e32 v217, v125
	v_mov_b32_e32 v212, v97
	s_waitcnt lgkmcnt(1)
	v_mul_f32_e32 v210, v125, v213
	s_waitcnt lgkmcnt(0)
	v_pk_fma_f32 v[212:213], v[216:217], v[212:213], v[210:211] op_sel_hi:[1,1,0]
	v_mov_b32_e32 v216, v121
	v_mov_b32_e32 v217, v117
	v_mov_b32_e32 v210, v93
	v_mul_f32_e32 v218, v117, v211
	v_pk_fma_f32 v[210:211], v[216:217], v[210:211], v[218:219] op_sel_hi:[1,1,0]
	v_mov_b32_e32 v97, v212
	v_mov_b32_e32 v93, v210

.LBB0_438:
	s_andn2_saveexec_b64 s[4:5], s[4:5]
	s_cbranch_execz .LBB0_440
	v_mov_b32_e32 v216, v129
	v_mov_b32_e32 v217, v125
	v_mov_b32_e32 v212, v97
	s_waitcnt lgkmcnt(1)
	v_mul_f32_e32 v210, v125, v213
	s_waitcnt lgkmcnt(0)
	v_pk_fma_f32 v[212:213], v[216:217], v[212:213], v[210:211] op_sel_hi:[1,1,0] neg_lo:[0,0,1] neg_hi:[0,0,1]
	v_mov_b32_e32 v216, v121
	v_mov_b32_e32 v217, v117
	v_mov_b32_e32 v210, v93
	v_mul_f32_e32 v218, v117, v211
	v_pk_fma_f32 v[210:211], v[216:217], v[210:211], v[218:219] op_sel_hi:[1,1,0] neg_lo:[0,0,1] neg_hi:[0,0,1]
	v_mov_b32_e32 v97, v212
	v_mov_b32_e32 v93, v210

.LBB0_441:
	s_waitcnt lgkmcnt(0)
	v_pk_mul_f32 v[210:211], v[94:95], s[36:37] op_sel_hi:[1,0]
	v_pk_mul_f32 v[216:217], v[90:91], s[36:37] op_sel_hi:[1,0]
	v_pk_mul_f32 v[212:213], v[96:97], s[36:37] op_sel_hi:[1,0]
	v_pk_mul_f32 v[218:219], v[92:93], s[36:37] op_sel_hi:[1,0]
	v_cndmask_b32_e64 v94, v94, v210, s[40:41]
	v_cndmask_b32_e64 v90, v90, v216, s[40:41]
	v_cndmask_b32_e64 v91, v91, v217, s[40:41]
	v_cndmask_b32_e64 v96, v96, v212, s[40:41]
	v_cndmask_b32_e64 v97, v97, v213, s[40:41]
	v_cndmask_b32_e64 v95, v95, v211, s[40:41]
	v_cndmask_b32_e64 v177, v92, v218, s[40:41]
	v_cndmask_b32_e64 v193, v93, v219, s[40:41]
	v_cvt_pk_bf16_f32 v92, v94, v95
	v_cvt_pk_bf16_f32 v93, v96, v97
	v_cvt_pk_bf16_f32 v94, v90, v91
	v_mov_b64_e32 v[90:91], s[62:63]
	s_movk_i32 s4, 0x1200
	v_mad_i64_i32 v[90:91], s[4:5], v206, s4, v[90:91]
	v_lshl_add_u64 v[96:97], v[0:1], 1, v[90:91]
	s_movk_i32 s4, 0xf000
	v_add_co_u32_e32 v96, vcc, s4, v96
	v_mov_b32_e32 v209, v208
	s_nop 0
	v_addc_co_u32_e32 v97, vcc, -1, v97, vcc
	v_cvt_pk_bf16_f32 v95, v177, v193
	flat_store_dwordx4 v[96:97], v[92:95] nt
	v_pk_mul_f32 v[86:87], v[86:87], v[208:209]
	s_and_b64 vcc, exec, s[46:47]
	v_mov_b32_e32 v92, v208
	v_mov_b32_e32 v93, v208
	v_pk_mul_f32 v[88:89], v[88:89], v[92:93]
	v_pk_mul_f32 v[84:85], v[84:85], v[92:93]
	v_pk_mul_f32 v[82:83], v[82:83], v[208:209]
	s_cbranch_vccnz .LBB0_467
	v_and_b32_e32 v93, 64, v226
	v_xor_b32_e32 v92, 16, v226
	v_add_u32_e32 v93, 64, v93
	v_cmp_lt_i32_e32 vcc, v92, v93
	s_nop 1
	v_cndmask_b32_e32 v92, v226, v92, vcc
	v_lshlrev_b32_e32 v96, 2, v92
	ds_bpermute_b32 v95, v96, v86
	ds_bpermute_b32 v93, v96, v82
	v_cmp_lt_i32_e32 vcc, 0, v233
	s_and_saveexec_b64 s[4:5], vcc
	s_xor_b64 s[4:5], exec, s[4:5]
	s_cbranch_execz .LBB0_446
	v_cmp_eq_u32_e32 vcc, 1, v233
	s_and_saveexec_b64 s[6:7], vcc
	s_cbranch_execz .LBB0_445
	v_mov_b32_e32 v206, v86
	v_mov_b32_e32 v207, v122
	v_mov_b32_e32 v94, v126
	s_waitcnt lgkmcnt(0)
	v_pk_mul_f32 v[94:95], v[206:207], v[94:95]
	v_mov_b32_e32 v206, v82
	v_mov_b32_e32 v207, v114
	v_mov_b32_e32 v92, v118
	v_pk_mul_f32 v[92:93], v[206:207], v[92:93]
	v_add_f32_e32 v86, v94, v95
	v_add_f32_e32 v82, v92, v93

.LBB0_446:
	s_andn2_saveexec_b64 s[4:5], s[4:5]
	s_cbranch_execz .LBB0_448
	v_mov_b32_e32 v206, v86
	v_mov_b32_e32 v207, v122
	v_mov_b32_e32 v94, v126
	s_waitcnt lgkmcnt(0)
	v_pk_mul_f32 v[94:95], v[206:207], v[94:95]
	v_mov_b32_e32 v206, v82
	v_mov_b32_e32 v207, v114
	v_mov_b32_e32 v92, v118
	v_pk_mul_f32 v[92:93], v[206:207], v[92:93]
	v_sub_f32_e32 v86, v94, v95
	v_sub_f32_e32 v82, v92, v93
.LBB0_448:
	s_or_b64 exec, exec, s[4:5]
	s_waitcnt lgkmcnt(0)
	ds_bpermute_b32 v95, v96, v87
	ds_bpermute_b32 v93, v96, v83
	v_cmp_lt_i32_e32 vcc, 0, v233
	s_and_saveexec_b64 s[4:5], vcc
	s_xor_b64 s[4:5], exec, s[4:5]
	s_cbranch_execz .LBB0_452
	v_cmp_eq_u32_e32 vcc, 1, v233
	s_and_saveexec_b64 s[6:7], vcc
	s_cbranch_execz .LBB0_451
	v_mov_b32_e32 v206, v127
	v_mov_b32_e32 v207, v123
	v_mov_b32_e32 v94, v87
	v_mul_f32_e32 v92, v127, v87
	s_waitcnt lgkmcnt(0)
	v_pk_fma_f32 v[94:95], v[206:207], v[94:95], v[92:93] op_sel_hi:[1,1,0]
	v_mov_b32_e32 v206, v119
	v_mov_b32_e32 v207, v115
	v_mov_b32_e32 v92, v83
	v_mul_f32_e32 v94, v119, v83
	v_pk_fma_f32 v[92:93], v[206:207], v[92:93], v[94:95] op_sel_hi:[1,1,0]
	v_mov_b32_e32 v87, v95
	v_mov_b32_e32 v83, v93

.LBB0_452:
	s_andn2_saveexec_b64 s[4:5], s[4:5]
	s_cbranch_execz .LBB0_454
	v_mov_b32_e32 v206, v127
	v_mov_b32_e32 v207, v123
	v_mov_b32_e32 v94, v87
	v_mul_f32_e32 v92, v127, v87
	s_waitcnt lgkmcnt(0)
	v_pk_fma_f32 v[94:95], v[206:207], v[94:95], v[92:93] op_sel_hi:[1,1,0] neg_lo:[1,0,0] neg_hi:[1,0,0]
	v_mov_b32_e32 v206, v119
	v_mov_b32_e32 v207, v115
	v_mov_b32_e32 v92, v83
	v_mul_f32_e32 v94, v119, v83
	v_pk_fma_f32 v[92:93], v[206:207], v[92:93], v[94:95] op_sel_hi:[1,1,0] neg_lo:[1,0,0] neg_hi:[1,0,0]
	v_mov_b32_e32 v87, v95
	v_mov_b32_e32 v83, v93
.LBB0_454:
	s_or_b64 exec, exec, s[4:5]
	s_waitcnt lgkmcnt(0)
	ds_bpermute_b32 v95, v96, v88
	ds_bpermute_b32 v93, v96, v84
	v_cmp_lt_i32_e32 vcc, 0, v233
	s_and_saveexec_b64 s[4:5], vcc
	s_xor_b64 s[4:5], exec, s[4:5]
	s_cbranch_execz .LBB0_458
	v_cmp_eq_u32_e32 vcc, 1, v233
	s_and_saveexec_b64 s[6:7], vcc
	s_cbranch_execz .LBB0_457
	v_mov_b32_e32 v206, v128
	v_mov_b32_e32 v207, v124
	v_mov_b32_e32 v94, v88
	s_waitcnt lgkmcnt(1)
	v_mul_f32_e32 v88, v124, v95
	v_pk_fma_f32 v[94:95], v[206:207], v[94:95], v[88:89] op_sel_hi:[1,1,0]
	v_mov_b32_e32 v206, v120
	v_mov_b32_e32 v207, v116
	v_mov_b32_e32 v92, v84
	s_waitcnt lgkmcnt(0)
	v_mul_f32_e32 v84, v116, v93
	v_pk_fma_f32 v[92:93], v[206:207], v[92:93], v[84:85] op_sel_hi:[1,1,0]
	v_mov_b32_e32 v88, v94
	v_mov_b32_e32 v84, v92

.LBB0_458:
	s_andn2_saveexec_b64 s[4:5], s[4:5]
	s_cbranch_execz .LBB0_460
	v_mov_b32_e32 v206, v128
	v_mov_b32_e32 v207, v124
	v_mov_b32_e32 v94, v88
	s_waitcnt lgkmcnt(1)
	v_mul_f32_e32 v88, v124, v95
	v_pk_fma_f32 v[94:95], v[206:207], v[94:95], v[88:89] op_sel_hi:[1,1,0] neg_lo:[0,0,1] neg_hi:[0,0,1]
	v_mov_b32_e32 v206, v120
	v_mov_b32_e32 v207, v116
	v_mov_b32_e32 v92, v84
	s_waitcnt lgkmcnt(0)
	v_mul_f32_e32 v84, v116, v93
	v_pk_fma_f32 v[92:93], v[206:207], v[92:93], v[84:85] op_sel_hi:[1,1,0] neg_lo:[0,0,1] neg_hi:[0,0,1]
	v_mov_b32_e32 v88, v94
	v_mov_b32_e32 v84, v92
.LBB0_460:
	s_or_b64 exec, exec, s[4:5]
	s_waitcnt lgkmcnt(0)
	ds_bpermute_b32 v95, v96, v89
	ds_bpermute_b32 v93, v96, v85
	v_cmp_lt_i32_e32 vcc, 0, v233
	s_and_saveexec_b64 s[4:5], vcc
	s_xor_b64 s[4:5], exec, s[4:5]
	s_cbranch_execz .LBB0_464
	v_cmp_eq_u32_e32 vcc, 1, v233
	s_and_saveexec_b64 s[6:7], vcc
	s_cbranch_execz .LBB0_463
	v_mov_b32_e32 v96, v129
	v_mov_b32_e32 v97, v125
	v_mov_b32_e32 v94, v89
	s_waitcnt lgkmcnt(1)
	v_mul_f32_e32 v92, v125, v95
	s_waitcnt lgkmcnt(0)
	v_pk_fma_f32 v[94:95], v[96:97], v[94:95], v[92:93] op_sel_hi:[1,1,0]
	v_mov_b32_e32 v96, v121
	v_mov_b32_e32 v97, v117
	v_mov_b32_e32 v92, v85
	v_mul_f32_e32 v206, v117, v93
	v_pk_fma_f32 v[92:93], v[96:97], v[92:93], v[206:207] op_sel_hi:[1,1,0]
	v_mov_b32_e32 v89, v94
	v_mov_b32_e32 v85, v92

.LBB0_464:
	s_andn2_saveexec_b64 s[4:5], s[4:5]
	s_cbranch_execz .LBB0_466
	v_mov_b32_e32 v96, v129
	v_mov_b32_e32 v97, v125
	v_mov_b32_e32 v94, v89
	s_waitcnt lgkmcnt(1)
	v_mul_f32_e32 v92, v125, v95
	s_waitcnt lgkmcnt(0)
	v_pk_fma_f32 v[94:95], v[96:97], v[94:95], v[92:93] op_sel_hi:[1,1,0] neg_lo:[0,0,1] neg_hi:[0,0,1]
	v_mov_b32_e32 v96, v121
	v_mov_b32_e32 v97, v117
	v_mov_b32_e32 v92, v85
	v_mul_f32_e32 v206, v117, v93
	v_pk_fma_f32 v[92:93], v[96:97], v[92:93], v[206:207] op_sel_hi:[1,1,0] neg_lo:[0,0,1] neg_hi:[0,0,1]
	v_mov_b32_e32 v89, v94
	v_mov_b32_e32 v85, v92

.LBB0_467:
	s_waitcnt lgkmcnt(0)
	v_pk_mul_f32 v[92:93], v[86:87], s[36:37] op_sel_hi:[1,0]
	v_pk_mul_f32 v[96:97], v[82:83], s[36:37] op_sel_hi:[1,0]
	v_pk_mul_f32 v[206:207], v[84:85], s[36:37] op_sel_hi:[1,0]
	v_cndmask_b32_e64 v86, v86, v92, s[44:45]
	v_cndmask_b32_e64 v87, v87, v93, s[44:45]
	v_cndmask_b32_e64 v92, v84, v206, s[44:45]
	v_cndmask_b32_e64 v84, v82, v96, s[44:45]
	v_cvt_pk_bf16_f32 v82, v86, v87
	v_lshl_add_u64 v[86:87], v[214:215], 1, v[90:91]
	s_movk_i32 s4, 0xf100
	v_add_co_u32_e32 v86, vcc, s4, v86
	v_pk_mul_f32 v[94:95], v[88:89], s[36:37] op_sel_hi:[1,0]
	s_nop 0
	v_addc_co_u32_e32 v87, vcc, -1, v87, vcc
	v_cndmask_b32_e64 v85, v85, v207, s[44:45]
	v_pk_mul_f32 v[80:81], v[80:81], v[204:205] op_sel_hi:[1,0]
	v_pk_mul_f32 v[78:79], v[78:79], v[204:205] op_sel_hi:[1,0]
	v_pk_mul_f32 v[76:77], v[76:77], v[204:205] op_sel_hi:[1,0]
	s_and_b64 vcc, exec, s[42:43]
	v_pk_mul_f32 v[74:75], v[74:75], v[204:205] op_sel_hi:[1,0]
	v_cndmask_b32_e64 v88, v88, v94, s[44:45]
	v_cndmask_b32_e64 v89, v89, v95, s[44:45]
	v_cndmask_b32_e64 v93, v83, v97, s[44:45]
	v_cvt_pk_bf16_f32 v83, v88, v89
	v_cvt_pk_bf16_f32 v84, v84, v93
	v_cvt_pk_bf16_f32 v85, v92, v85
	flat_store_dwordx4 v[86:87], v[82:85] nt
	s_cbranch_vccnz .LBB0_493
	s_nop 0
	v_and_b32_e32 v83, 64, v226
	v_xor_b32_e32 v82, 16, v226
	v_add_u32_e32 v83, 64, v83
	v_cmp_lt_i32_e32 vcc, v82, v83
	s_nop 1
	v_cndmask_b32_e32 v82, v226, v82, vcc
	v_lshlrev_b32_e32 v86, 2, v82
	ds_bpermute_b32 v85, v86, v78
	ds_bpermute_b32 v83, v86, v74
	v_cmp_lt_i32_e32 vcc, 0, v233
	s_and_saveexec_b64 s[4:5], vcc
	s_xor_b64 s[4:5], exec, s[4:5]
	s_cbranch_execz .LBB0_472
	v_cmp_eq_u32_e32 vcc, 1, v233
	s_and_saveexec_b64 s[6:7], vcc
	s_cbranch_execz .LBB0_471
	v_mov_b32_e32 v88, v78
	v_mov_b32_e32 v89, v106
	v_mov_b32_e32 v84, v110
	s_waitcnt lgkmcnt(0)
	v_pk_mul_f32 v[84:85], v[88:89], v[84:85]
	v_mov_b32_e32 v88, v74
	v_mov_b32_e32 v89, v98
	v_mov_b32_e32 v82, v102
	v_pk_mul_f32 v[82:83], v[88:89], v[82:83]
	v_add_f32_e32 v78, v84, v85
	v_add_f32_e32 v74, v82, v83

.LBB0_472:
	s_andn2_saveexec_b64 s[4:5], s[4:5]
	s_cbranch_execz .LBB0_474
	v_mov_b32_e32 v88, v78
	v_mov_b32_e32 v89, v106
	v_mov_b32_e32 v84, v110
	s_waitcnt lgkmcnt(0)
	v_pk_mul_f32 v[84:85], v[88:89], v[84:85]
	v_mov_b32_e32 v88, v74
	v_mov_b32_e32 v89, v98
	v_mov_b32_e32 v82, v102
	v_pk_mul_f32 v[82:83], v[88:89], v[82:83]
	v_sub_f32_e32 v78, v84, v85
	v_sub_f32_e32 v74, v82, v83
.LBB0_474:
	s_or_b64 exec, exec, s[4:5]
	s_waitcnt lgkmcnt(0)
	ds_bpermute_b32 v85, v86, v79
	ds_bpermute_b32 v83, v86, v75
	v_cmp_lt_i32_e32 vcc, 0, v233
	s_and_saveexec_b64 s[4:5], vcc
	s_xor_b64 s[4:5], exec, s[4:5]
	s_cbranch_execz .LBB0_478
	v_cmp_eq_u32_e32 vcc, 1, v233
	s_and_saveexec_b64 s[6:7], vcc
	s_cbranch_execz .LBB0_477
	v_mov_b32_e32 v88, v111
	v_mov_b32_e32 v89, v107
	v_mov_b32_e32 v84, v79
	v_mul_f32_e32 v82, v111, v79
	s_waitcnt lgkmcnt(0)
	v_pk_fma_f32 v[84:85], v[88:89], v[84:85], v[82:83] op_sel_hi:[1,1,0]
	v_mov_b32_e32 v88, v103
	v_mov_b32_e32 v89, v99
	v_mov_b32_e32 v82, v75
	v_mul_f32_e32 v84, v103, v75
	v_pk_fma_f32 v[82:83], v[88:89], v[82:83], v[84:85] op_sel_hi:[1,1,0]
	v_mov_b32_e32 v79, v85
	v_mov_b32_e32 v75, v83

.LBB0_478:
	s_andn2_saveexec_b64 s[4:5], s[4:5]
	s_cbranch_execz .LBB0_480
	v_mov_b32_e32 v88, v111
	v_mov_b32_e32 v89, v107
	v_mov_b32_e32 v84, v79
	v_mul_f32_e32 v82, v111, v79
	s_waitcnt lgkmcnt(0)
	v_pk_fma_f32 v[84:85], v[88:89], v[84:85], v[82:83] op_sel_hi:[1,1,0] neg_lo:[1,0,0] neg_hi:[1,0,0]
	v_mov_b32_e32 v88, v103
	v_mov_b32_e32 v89, v99
	v_mov_b32_e32 v82, v75
	v_mul_f32_e32 v84, v103, v75
	v_pk_fma_f32 v[82:83], v[88:89], v[82:83], v[84:85] op_sel_hi:[1,1,0] neg_lo:[1,0,0] neg_hi:[1,0,0]
	v_mov_b32_e32 v79, v85
	v_mov_b32_e32 v75, v83
.LBB0_480:
	s_or_b64 exec, exec, s[4:5]
	s_waitcnt lgkmcnt(0)
	ds_bpermute_b32 v85, v86, v80
	ds_bpermute_b32 v83, v86, v76
	v_cmp_lt_i32_e32 vcc, 0, v233
	s_and_saveexec_b64 s[4:5], vcc
	s_xor_b64 s[4:5], exec, s[4:5]
	s_cbranch_execz .LBB0_484
	v_cmp_eq_u32_e32 vcc, 1, v233
	s_and_saveexec_b64 s[6:7], vcc
	s_cbranch_execz .LBB0_483
	v_mov_b32_e32 v88, v112
	v_mov_b32_e32 v89, v108
	v_mov_b32_e32 v84, v80
	s_waitcnt lgkmcnt(1)
	v_mul_f32_e32 v80, v108, v85
	v_pk_fma_f32 v[84:85], v[88:89], v[84:85], v[80:81] op_sel_hi:[1,1,0]
	v_mov_b32_e32 v88, v104
	v_mov_b32_e32 v89, v100
	v_mov_b32_e32 v82, v76
	s_waitcnt lgkmcnt(0)
	v_mul_f32_e32 v76, v100, v83
	v_pk_fma_f32 v[82:83], v[88:89], v[82:83], v[76:77] op_sel_hi:[1,1,0]
	v_mov_b32_e32 v80, v84
	v_mov_b32_e32 v76, v82

.LBB0_484:
	s_andn2_saveexec_b64 s[4:5], s[4:5]
	s_cbranch_execz .LBB0_486
	v_mov_b32_e32 v88, v112
	v_mov_b32_e32 v89, v108
	v_mov_b32_e32 v84, v80
	s_waitcnt lgkmcnt(1)
	v_mul_f32_e32 v80, v108, v85
	v_pk_fma_f32 v[84:85], v[88:89], v[84:85], v[80:81] op_sel_hi:[1,1,0] neg_lo:[0,0,1] neg_hi:[0,0,1]
	v_mov_b32_e32 v88, v104
	v_mov_b32_e32 v89, v100
	v_mov_b32_e32 v82, v76
	s_waitcnt lgkmcnt(0)
	v_mul_f32_e32 v76, v100, v83
	v_pk_fma_f32 v[82:83], v[88:89], v[82:83], v[76:77] op_sel_hi:[1,1,0] neg_lo:[0,0,1] neg_hi:[0,0,1]
	v_mov_b32_e32 v80, v84
	v_mov_b32_e32 v76, v82
.LBB0_486:
	s_or_b64 exec, exec, s[4:5]
	s_waitcnt lgkmcnt(0)
	ds_bpermute_b32 v85, v86, v81
	ds_bpermute_b32 v83, v86, v77
	v_cmp_lt_i32_e32 vcc, 0, v233
	s_and_saveexec_b64 s[4:5], vcc
	s_xor_b64 s[4:5], exec, s[4:5]
	s_cbranch_execz .LBB0_490
	v_cmp_eq_u32_e32 vcc, 1, v233
	s_and_saveexec_b64 s[6:7], vcc
	s_cbranch_execz .LBB0_489
	v_mov_b32_e32 v86, v113
	v_mov_b32_e32 v87, v109
	v_mov_b32_e32 v84, v81
	s_waitcnt lgkmcnt(1)
	v_mul_f32_e32 v82, v109, v85
	s_waitcnt lgkmcnt(0)
	v_pk_fma_f32 v[84:85], v[86:87], v[84:85], v[82:83] op_sel_hi:[1,1,0]
	v_mov_b32_e32 v86, v105
	v_mov_b32_e32 v87, v101
	v_mov_b32_e32 v82, v77
	v_mul_f32_e32 v88, v101, v83
	v_pk_fma_f32 v[82:83], v[86:87], v[82:83], v[88:89] op_sel_hi:[1,1,0]
	v_mov_b32_e32 v81, v84
	v_mov_b32_e32 v77, v82

.LBB0_490:
	s_andn2_saveexec_b64 s[4:5], s[4:5]
	s_cbranch_execz .LBB0_492
	v_mov_b32_e32 v86, v113
	v_mov_b32_e32 v87, v109
	v_mov_b32_e32 v84, v81
	s_waitcnt lgkmcnt(1)
	v_mul_f32_e32 v82, v109, v85
	s_waitcnt lgkmcnt(0)
	v_pk_fma_f32 v[84:85], v[86:87], v[84:85], v[82:83] op_sel_hi:[1,1,0] neg_lo:[0,0,1] neg_hi:[0,0,1]
	v_mov_b32_e32 v86, v105
	v_mov_b32_e32 v87, v101
	v_mov_b32_e32 v82, v77
	v_mul_f32_e32 v88, v101, v83
	v_pk_fma_f32 v[82:83], v[86:87], v[82:83], v[88:89] op_sel_hi:[1,1,0] neg_lo:[0,0,1] neg_hi:[0,0,1]
	v_mov_b32_e32 v81, v84
	v_mov_b32_e32 v77, v82

.LBB0_493:
	s_waitcnt lgkmcnt(0)
	v_pk_mul_f32 v[82:83], v[78:79], s[36:37] op_sel_hi:[1,0]
	v_pk_mul_f32 v[86:87], v[74:75], s[36:37] op_sel_hi:[1,0]
	v_pk_mul_f32 v[84:85], v[80:81], s[36:37] op_sel_hi:[1,0]
	v_pk_mul_f32 v[88:89], v[76:77], s[36:37] op_sel_hi:[1,0]
	v_cndmask_b32_e64 v78, v78, v82, s[40:41]
	v_cndmask_b32_e64 v74, v74, v86, s[40:41]
	v_cndmask_b32_e64 v75, v75, v87, s[40:41]
	v_cndmask_b32_e64 v80, v80, v84, s[40:41]
	v_cndmask_b32_e64 v81, v81, v85, s[40:41]
	v_cndmask_b32_e64 v79, v79, v83, s[40:41]
	v_cndmask_b32_e64 v82, v76, v88, s[40:41]
	v_cndmask_b32_e64 v83, v77, v89, s[40:41]
	v_cvt_pk_bf16_f32 v76, v78, v79
	v_cvt_pk_bf16_f32 v77, v80, v81
	v_cvt_pk_bf16_f32 v78, v74, v75
	v_mov_b64_e32 v[74:75], s[62:63]
	s_movk_i32 s4, 0x1200
	v_mad_i64_i32 v[74:75], s[4:5], v202, s4, v[74:75]
	v_lshl_add_u64 v[80:81], v[0:1], 1, v[74:75]
	s_movk_i32 s4, 0xf000
	v_add_co_u32_e32 v80, vcc, s4, v80
	v_mov_b32_e32 v205, v204
	s_nop 0
	v_addc_co_u32_e32 v81, vcc, -1, v81, vcc
	v_cvt_pk_bf16_f32 v79, v82, v83
	flat_store_dwordx4 v[80:81], v[76:79] nt
	v_pk_mul_f32 v[70:71], v[70:71], v[204:205]
	s_and_b64 vcc, exec, s[46:47]
	v_mov_b32_e32 v76, v204
	v_mov_b32_e32 v77, v204
	v_pk_mul_f32 v[72:73], v[72:73], v[76:77]
	v_pk_mul_f32 v[68:69], v[68:69], v[76:77]
	v_pk_mul_f32 v[66:67], v[66:67], v[204:205]
	s_cbranch_vccnz .LBB0_519
	v_and_b32_e32 v77, 64, v226
	v_xor_b32_e32 v76, 16, v226
	v_add_u32_e32 v77, 64, v77
	v_cmp_lt_i32_e32 vcc, v76, v77
	s_nop 1
	v_cndmask_b32_e32 v76, v226, v76, vcc
	v_lshlrev_b32_e32 v80, 2, v76
	ds_bpermute_b32 v79, v80, v70
	ds_bpermute_b32 v77, v80, v66
	v_cmp_lt_i32_e32 vcc, 0, v233
	s_and_saveexec_b64 s[4:5], vcc
	s_xor_b64 s[4:5], exec, s[4:5]
	s_cbranch_execz .LBB0_498
	v_cmp_eq_u32_e32 vcc, 1, v233
	s_and_saveexec_b64 s[6:7], vcc
	s_cbranch_execz .LBB0_497
	v_mov_b32_e32 v82, v70
	v_mov_b32_e32 v83, v106
	v_mov_b32_e32 v78, v110
	s_waitcnt lgkmcnt(0)
	v_pk_mul_f32 v[78:79], v[82:83], v[78:79]
	v_mov_b32_e32 v82, v66
	v_mov_b32_e32 v83, v98
	v_mov_b32_e32 v76, v102
	v_pk_mul_f32 v[76:77], v[82:83], v[76:77]
	v_add_f32_e32 v70, v78, v79
	v_add_f32_e32 v66, v76, v77

.LBB0_498:
	s_andn2_saveexec_b64 s[4:5], s[4:5]
	s_cbranch_execz .LBB0_500
	v_mov_b32_e32 v82, v70
	v_mov_b32_e32 v83, v106
	v_mov_b32_e32 v78, v110
	s_waitcnt lgkmcnt(0)
	v_pk_mul_f32 v[78:79], v[82:83], v[78:79]
	v_mov_b32_e32 v82, v66
	v_mov_b32_e32 v83, v98
	v_mov_b32_e32 v76, v102
	v_pk_mul_f32 v[76:77], v[82:83], v[76:77]
	v_sub_f32_e32 v70, v78, v79
	v_sub_f32_e32 v66, v76, v77
.LBB0_500:
	s_or_b64 exec, exec, s[4:5]
	s_waitcnt lgkmcnt(0)
	ds_bpermute_b32 v79, v80, v71
	ds_bpermute_b32 v77, v80, v67
	v_cmp_lt_i32_e32 vcc, 0, v233
	s_and_saveexec_b64 s[4:5], vcc
	s_xor_b64 s[4:5], exec, s[4:5]
	s_cbranch_execz .LBB0_504
	v_cmp_eq_u32_e32 vcc, 1, v233
	s_and_saveexec_b64 s[6:7], vcc
	s_cbranch_execz .LBB0_503
	v_mov_b32_e32 v82, v111
	v_mov_b32_e32 v83, v107
	v_mov_b32_e32 v78, v71
	v_mul_f32_e32 v76, v111, v71
	s_waitcnt lgkmcnt(0)
	v_pk_fma_f32 v[78:79], v[82:83], v[78:79], v[76:77] op_sel_hi:[1,1,0]
	v_mov_b32_e32 v82, v103
	v_mov_b32_e32 v83, v99
	v_mov_b32_e32 v76, v67
	v_mul_f32_e32 v78, v103, v67
	v_pk_fma_f32 v[76:77], v[82:83], v[76:77], v[78:79] op_sel_hi:[1,1,0]
	v_mov_b32_e32 v71, v79
	v_mov_b32_e32 v67, v77

.LBB0_504:
	s_andn2_saveexec_b64 s[4:5], s[4:5]
	s_cbranch_execz .LBB0_506
	v_mov_b32_e32 v82, v111
	v_mov_b32_e32 v83, v107
	v_mov_b32_e32 v78, v71
	v_mul_f32_e32 v76, v111, v71
	s_waitcnt lgkmcnt(0)
	v_pk_fma_f32 v[78:79], v[82:83], v[78:79], v[76:77] op_sel_hi:[1,1,0] neg_lo:[1,0,0] neg_hi:[1,0,0]
	v_mov_b32_e32 v82, v103
	v_mov_b32_e32 v83, v99
	v_mov_b32_e32 v76, v67
	v_mul_f32_e32 v78, v103, v67
	v_pk_fma_f32 v[76:77], v[82:83], v[76:77], v[78:79] op_sel_hi:[1,1,0] neg_lo:[1,0,0] neg_hi:[1,0,0]
	v_mov_b32_e32 v71, v79
	v_mov_b32_e32 v67, v77
.LBB0_506:
	s_or_b64 exec, exec, s[4:5]
	s_waitcnt lgkmcnt(0)
	ds_bpermute_b32 v79, v80, v72
	ds_bpermute_b32 v77, v80, v68
	v_cmp_lt_i32_e32 vcc, 0, v233
	s_and_saveexec_b64 s[4:5], vcc
	s_xor_b64 s[4:5], exec, s[4:5]
	s_cbranch_execz .LBB0_510
	v_cmp_eq_u32_e32 vcc, 1, v233
	s_and_saveexec_b64 s[6:7], vcc
	s_cbranch_execz .LBB0_509
	v_mov_b32_e32 v82, v112
	v_mov_b32_e32 v83, v108
	v_mov_b32_e32 v78, v72
	s_waitcnt lgkmcnt(1)
	v_mul_f32_e32 v72, v108, v79
	v_pk_fma_f32 v[78:79], v[82:83], v[78:79], v[72:73] op_sel_hi:[1,1,0]
	v_mov_b32_e32 v82, v104
	v_mov_b32_e32 v83, v100
	v_mov_b32_e32 v76, v68
	s_waitcnt lgkmcnt(0)
	v_mul_f32_e32 v68, v100, v77
	v_pk_fma_f32 v[76:77], v[82:83], v[76:77], v[68:69] op_sel_hi:[1,1,0]
	v_mov_b32_e32 v72, v78
	v_mov_b32_e32 v68, v76

.LBB0_510:
	s_andn2_saveexec_b64 s[4:5], s[4:5]
	s_cbranch_execz .LBB0_512
	v_mov_b32_e32 v82, v112
	v_mov_b32_e32 v83, v108
	v_mov_b32_e32 v78, v72
	s_waitcnt lgkmcnt(1)
	v_mul_f32_e32 v72, v108, v79
	v_pk_fma_f32 v[78:79], v[82:83], v[78:79], v[72:73] op_sel_hi:[1,1,0] neg_lo:[0,0,1] neg_hi:[0,0,1]
	v_mov_b32_e32 v82, v104
	v_mov_b32_e32 v83, v100
	v_mov_b32_e32 v76, v68
	s_waitcnt lgkmcnt(0)
	v_mul_f32_e32 v68, v100, v77
	v_pk_fma_f32 v[76:77], v[82:83], v[76:77], v[68:69] op_sel_hi:[1,1,0] neg_lo:[0,0,1] neg_hi:[0,0,1]
	v_mov_b32_e32 v72, v78
	v_mov_b32_e32 v68, v76
.LBB0_512:
	s_or_b64 exec, exec, s[4:5]
	s_waitcnt lgkmcnt(0)
	ds_bpermute_b32 v79, v80, v73
	ds_bpermute_b32 v77, v80, v69
	v_cmp_lt_i32_e32 vcc, 0, v233
	s_and_saveexec_b64 s[4:5], vcc
	s_xor_b64 s[4:5], exec, s[4:5]
	s_cbranch_execz .LBB0_516
	v_cmp_eq_u32_e32 vcc, 1, v233
	s_and_saveexec_b64 s[6:7], vcc
	s_cbranch_execz .LBB0_515
	v_mov_b32_e32 v80, v113
	v_mov_b32_e32 v81, v109
	v_mov_b32_e32 v78, v73
	s_waitcnt lgkmcnt(1)
	v_mul_f32_e32 v76, v109, v79
	s_waitcnt lgkmcnt(0)
	v_pk_fma_f32 v[78:79], v[80:81], v[78:79], v[76:77] op_sel_hi:[1,1,0]
	v_mov_b32_e32 v80, v105
	v_mov_b32_e32 v81, v101
	v_mov_b32_e32 v76, v69
	v_mul_f32_e32 v82, v101, v77
	v_pk_fma_f32 v[76:77], v[80:81], v[76:77], v[82:83] op_sel_hi:[1,1,0]
	v_mov_b32_e32 v73, v78
	v_mov_b32_e32 v69, v76

.LBB0_516:
	s_andn2_saveexec_b64 s[4:5], s[4:5]
	s_cbranch_execz .LBB0_518
	v_mov_b32_e32 v80, v113
	v_mov_b32_e32 v81, v109
	v_mov_b32_e32 v78, v73
	s_waitcnt lgkmcnt(1)
	v_mul_f32_e32 v76, v109, v79
	s_waitcnt lgkmcnt(0)
	v_pk_fma_f32 v[78:79], v[80:81], v[78:79], v[76:77] op_sel_hi:[1,1,0] neg_lo:[0,0,1] neg_hi:[0,0,1]
	v_mov_b32_e32 v80, v105
	v_mov_b32_e32 v81, v101
	v_mov_b32_e32 v76, v69
	v_mul_f32_e32 v82, v101, v77
	v_pk_fma_f32 v[76:77], v[80:81], v[76:77], v[82:83] op_sel_hi:[1,1,0] neg_lo:[0,0,1] neg_hi:[0,0,1]
	v_mov_b32_e32 v73, v78
	v_mov_b32_e32 v69, v76

.LBB0_519:
	s_waitcnt lgkmcnt(0)
	v_pk_mul_f32 v[76:77], v[70:71], s[36:37] op_sel_hi:[1,0]
	v_pk_mul_f32 v[80:81], v[66:67], s[36:37] op_sel_hi:[1,0]
	v_pk_mul_f32 v[82:83], v[68:69], s[36:37] op_sel_hi:[1,0]
	v_cndmask_b32_e64 v70, v70, v76, s[44:45]
	v_cndmask_b32_e64 v71, v71, v77, s[44:45]
	v_cndmask_b32_e64 v76, v68, v82, s[44:45]
	v_cndmask_b32_e64 v68, v66, v80, s[44:45]
	v_cvt_pk_bf16_f32 v66, v70, v71
	v_lshl_add_u64 v[70:71], v[214:215], 1, v[74:75]
	v_add_co_u32_e32 v70, vcc, 0xfffff100, v70
	v_pk_mul_f32 v[78:79], v[72:73], s[36:37] op_sel_hi:[1,0]
	s_nop 0
	v_addc_co_u32_e32 v71, vcc, -1, v71, vcc
	v_cndmask_b32_e64 v69, v69, v83, s[44:45]
	s_and_b64 vcc, exec, s[48:49]
	v_cndmask_b32_e64 v72, v72, v78, s[44:45]
	v_cndmask_b32_e64 v73, v73, v79, s[44:45]
	v_cndmask_b32_e64 v77, v67, v81, s[44:45]
	v_cvt_pk_bf16_f32 v67, v72, v73
	v_cvt_pk_bf16_f32 v68, v68, v77
	v_cvt_pk_bf16_f32 v69, v76, v69
	flat_store_dwordx4 v[70:71], v[66:69] nt
	s_cbranch_vccnz .LBB0_521
	s_nop 0
	v_lshlrev_b64 v[66:67], 6, v[198:199]
	v_lshl_add_u64 v[66:67], s[64:65], 0, v[66:67]
	flat_load_dwordx4 v[158:161], v[66:67]
	flat_load_dwordx4 v[150:153], v[66:67] offset:16
	flat_load_dwordx4 v[154:157], v[66:67] offset:32
	flat_load_dwordx4 v[146:149], v[66:67] offset:48
	v_lshlrev_b64 v[66:67], 6, v[194:195]
	v_lshl_add_u64 v[66:67], s[64:65], 0, v[66:67]
	flat_load_dwordx4 v[142:145], v[66:67]
	flat_load_dwordx4 v[134:137], v[66:67] offset:16
	flat_load_dwordx4 v[138:141], v[66:67] offset:32
	flat_load_dwordx4 v[130:133], v[66:67] offset:48
.LBB0_521:
	s_waitcnt vmcnt(0)
	v_pk_mul_f32 v[64:65], v[64:65], v[200:201] op_sel_hi:[1,0]
	v_pk_mul_f32 v[62:63], v[62:63], v[200:201] op_sel_hi:[1,0]
	v_pk_mul_f32 v[60:61], v[60:61], v[200:201] op_sel_hi:[1,0]
	s_and_b64 vcc, exec, s[42:43]
	v_pk_mul_f32 v[58:59], v[58:59], v[200:201] op_sel_hi:[1,0]
	s_cbranch_vccnz .LBB0_547
	v_and_b32_e32 v67, 64, v226
	v_xor_b32_e32 v66, 16, v226
	v_add_u32_e32 v67, 64, v67
	v_cmp_lt_i32_e32 vcc, v66, v67
	s_nop 1
	v_cndmask_b32_e32 v66, v226, v66, vcc
	v_lshlrev_b32_e32 v70, 2, v66
	ds_bpermute_b32 v69, v70, v62
	ds_bpermute_b32 v67, v70, v58
	v_cmp_lt_i32_e32 vcc, 0, v233
	s_and_saveexec_b64 s[4:5], vcc
	s_xor_b64 s[4:5], exec, s[4:5]
	s_cbranch_execz .LBB0_526
	v_cmp_eq_u32_e32 vcc, 1, v233
	s_and_saveexec_b64 s[6:7], vcc
	s_cbranch_execz .LBB0_525
	v_mov_b32_e32 v72, v62
	s_waitcnt lgkmcnt(0)
	v_mov_b32_e32 v73, v154
	v_mov_b32_e32 v68, v158
	v_pk_mul_f32 v[68:69], v[72:73], v[68:69]
	v_mov_b32_e32 v72, v58
	v_mov_b32_e32 v73, v146
	v_mov_b32_e32 v66, v150
	v_pk_mul_f32 v[66:67], v[72:73], v[66:67]
	v_add_f32_e32 v62, v68, v69
	v_add_f32_e32 v58, v66, v67

.LBB0_526:
	s_andn2_saveexec_b64 s[4:5], s[4:5]
	s_cbranch_execz .LBB0_528
	v_mov_b32_e32 v72, v62
	s_waitcnt lgkmcnt(0)
	v_mov_b32_e32 v73, v154
	v_mov_b32_e32 v68, v158
	v_pk_mul_f32 v[68:69], v[72:73], v[68:69]
	v_mov_b32_e32 v72, v58
	v_mov_b32_e32 v73, v146
	v_mov_b32_e32 v66, v150
	v_pk_mul_f32 v[66:67], v[72:73], v[66:67]
	v_sub_f32_e32 v62, v68, v69
	v_sub_f32_e32 v58, v66, v67
.LBB0_528:
	s_or_b64 exec, exec, s[4:5]
	s_waitcnt lgkmcnt(0)
	ds_bpermute_b32 v69, v70, v63
	ds_bpermute_b32 v67, v70, v59
	v_cmp_lt_i32_e32 vcc, 0, v233
	s_and_saveexec_b64 s[4:5], vcc
	s_xor_b64 s[4:5], exec, s[4:5]
	s_cbranch_execz .LBB0_532
	v_cmp_eq_u32_e32 vcc, 1, v233
	s_and_saveexec_b64 s[6:7], vcc
	s_cbranch_execz .LBB0_531
	v_mov_b32_e32 v72, v159
	v_mov_b32_e32 v73, v155
	v_mov_b32_e32 v68, v63
	v_mul_f32_e32 v66, v159, v63
	s_waitcnt lgkmcnt(0)
	v_pk_fma_f32 v[68:69], v[72:73], v[68:69], v[66:67] op_sel_hi:[1,1,0]
	v_mov_b32_e32 v72, v151
	v_mov_b32_e32 v73, v147
	v_mov_b32_e32 v66, v59
	v_mul_f32_e32 v68, v151, v59
	v_pk_fma_f32 v[66:67], v[72:73], v[66:67], v[68:69] op_sel_hi:[1,1,0]
	v_mov_b32_e32 v63, v69
	v_mov_b32_e32 v59, v67

.LBB0_532:
	s_andn2_saveexec_b64 s[4:5], s[4:5]
	s_cbranch_execz .LBB0_534
	v_mov_b32_e32 v72, v159
	v_mov_b32_e32 v73, v155
	v_mov_b32_e32 v68, v63
	v_mul_f32_e32 v66, v159, v63
	s_waitcnt lgkmcnt(0)
	v_pk_fma_f32 v[68:69], v[72:73], v[68:69], v[66:67] op_sel_hi:[1,1,0] neg_lo:[1,0,0] neg_hi:[1,0,0]
	v_mov_b32_e32 v72, v151
	v_mov_b32_e32 v73, v147
	v_mov_b32_e32 v66, v59
	v_mul_f32_e32 v68, v151, v59
	v_pk_fma_f32 v[66:67], v[72:73], v[66:67], v[68:69] op_sel_hi:[1,1,0] neg_lo:[1,0,0] neg_hi:[1,0,0]
	v_mov_b32_e32 v63, v69
	v_mov_b32_e32 v59, v67
.LBB0_534:
	s_or_b64 exec, exec, s[4:5]
	s_waitcnt lgkmcnt(0)
	ds_bpermute_b32 v69, v70, v64
	ds_bpermute_b32 v67, v70, v60
	v_cmp_lt_i32_e32 vcc, 0, v233
	s_and_saveexec_b64 s[4:5], vcc
	s_xor_b64 s[4:5], exec, s[4:5]
	s_cbranch_execz .LBB0_538
	v_cmp_eq_u32_e32 vcc, 1, v233
	s_and_saveexec_b64 s[6:7], vcc
	s_cbranch_execz .LBB0_537
	v_mov_b32_e32 v72, v160
	v_mov_b32_e32 v73, v156
	v_mov_b32_e32 v68, v64
	s_waitcnt lgkmcnt(1)
	v_mul_f32_e32 v64, v156, v69
	v_pk_fma_f32 v[68:69], v[72:73], v[68:69], v[64:65] op_sel_hi:[1,1,0]
	v_mov_b32_e32 v72, v152
	v_mov_b32_e32 v73, v148
	v_mov_b32_e32 v66, v60
	s_waitcnt lgkmcnt(0)
	v_mul_f32_e32 v60, v148, v67
	v_pk_fma_f32 v[66:67], v[72:73], v[66:67], v[60:61] op_sel_hi:[1,1,0]
	v_mov_b32_e32 v64, v68
	v_mov_b32_e32 v60, v66

.LBB0_538:
	s_andn2_saveexec_b64 s[4:5], s[4:5]
	s_cbranch_execz .LBB0_540
	v_mov_b32_e32 v72, v160
	v_mov_b32_e32 v73, v156
	v_mov_b32_e32 v68, v64
	s_waitcnt lgkmcnt(1)
	v_mul_f32_e32 v64, v156, v69
	v_pk_fma_f32 v[68:69], v[72:73], v[68:69], v[64:65] op_sel_hi:[1,1,0] neg_lo:[0,0,1] neg_hi:[0,0,1]
	v_mov_b32_e32 v72, v152
	v_mov_b32_e32 v73, v148
	v_mov_b32_e32 v66, v60
	s_waitcnt lgkmcnt(0)
	v_mul_f32_e32 v60, v148, v67
	v_pk_fma_f32 v[66:67], v[72:73], v[66:67], v[60:61] op_sel_hi:[1,1,0] neg_lo:[0,0,1] neg_hi:[0,0,1]
	v_mov_b32_e32 v64, v68
	v_mov_b32_e32 v60, v66
.LBB0_540:
	s_or_b64 exec, exec, s[4:5]
	s_waitcnt lgkmcnt(0)
	ds_bpermute_b32 v69, v70, v65
	ds_bpermute_b32 v67, v70, v61
	v_cmp_lt_i32_e32 vcc, 0, v233
	s_and_saveexec_b64 s[4:5], vcc
	s_xor_b64 s[4:5], exec, s[4:5]
	s_cbranch_execz .LBB0_544
	v_cmp_eq_u32_e32 vcc, 1, v233
	s_and_saveexec_b64 s[6:7], vcc
	s_cbranch_execz .LBB0_543
	v_mov_b32_e32 v70, v161
	v_mov_b32_e32 v71, v157
	v_mov_b32_e32 v68, v65
	s_waitcnt lgkmcnt(1)
	v_mul_f32_e32 v66, v157, v69
	s_waitcnt lgkmcnt(0)
	v_pk_fma_f32 v[68:69], v[70:71], v[68:69], v[66:67] op_sel_hi:[1,1,0]
	v_mov_b32_e32 v70, v153
	v_mov_b32_e32 v71, v149
	v_mov_b32_e32 v66, v61
	v_mul_f32_e32 v72, v149, v67
	v_pk_fma_f32 v[66:67], v[70:71], v[66:67], v[72:73] op_sel_hi:[1,1,0]
	v_mov_b32_e32 v65, v68
	v_mov_b32_e32 v61, v66

.LBB0_544:
	s_andn2_saveexec_b64 s[4:5], s[4:5]
	s_cbranch_execz .LBB0_546
	v_mov_b32_e32 v70, v161
	v_mov_b32_e32 v71, v157
	v_mov_b32_e32 v68, v65
	s_waitcnt lgkmcnt(1)
	v_mul_f32_e32 v66, v157, v69
	s_waitcnt lgkmcnt(0)
	v_pk_fma_f32 v[68:69], v[70:71], v[68:69], v[66:67] op_sel_hi:[1,1,0] neg_lo:[0,0,1] neg_hi:[0,0,1]
	v_mov_b32_e32 v70, v153
	v_mov_b32_e32 v71, v149
	v_mov_b32_e32 v66, v61
	v_mul_f32_e32 v72, v149, v67
	v_pk_fma_f32 v[66:67], v[70:71], v[66:67], v[72:73] op_sel_hi:[1,1,0] neg_lo:[0,0,1] neg_hi:[0,0,1]
	v_mov_b32_e32 v65, v68
	v_mov_b32_e32 v61, v66

.LBB0_547:
	s_waitcnt lgkmcnt(0)
	v_pk_mul_f32 v[66:67], v[62:63], s[36:37] op_sel_hi:[1,0]
	v_pk_mul_f32 v[70:71], v[58:59], s[36:37] op_sel_hi:[1,0]
	v_pk_mul_f32 v[68:69], v[64:65], s[36:37] op_sel_hi:[1,0]
	v_pk_mul_f32 v[72:73], v[60:61], s[36:37] op_sel_hi:[1,0]
	v_cndmask_b32_e64 v62, v62, v66, s[40:41]
	v_cndmask_b32_e64 v58, v58, v70, s[40:41]
	v_cndmask_b32_e64 v59, v59, v71, s[40:41]
	v_cndmask_b32_e64 v64, v64, v68, s[40:41]
	v_cndmask_b32_e64 v65, v65, v69, s[40:41]
	v_cndmask_b32_e64 v63, v63, v67, s[40:41]
	v_cndmask_b32_e64 v66, v60, v72, s[40:41]
	v_cndmask_b32_e64 v67, v61, v73, s[40:41]
	v_cvt_pk_bf16_f32 v60, v62, v63
	v_cvt_pk_bf16_f32 v61, v64, v65
	v_cvt_pk_bf16_f32 v62, v58, v59
	v_mov_b64_e32 v[58:59], s[62:63]
	s_movk_i32 s4, 0x1200
	v_mad_i64_i32 v[58:59], s[4:5], v198, s4, v[58:59]
	v_lshl_add_u64 v[64:65], v[0:1], 1, v[58:59]
	s_movk_i32 s4, 0xf000
	v_add_co_u32_e32 v64, vcc, s4, v64
	v_mov_b32_e32 v201, v200
	s_nop 0
	v_addc_co_u32_e32 v65, vcc, -1, v65, vcc
	v_cvt_pk_bf16_f32 v63, v66, v67
	flat_store_dwordx4 v[64:65], v[60:63] nt
	v_pk_mul_f32 v[54:55], v[54:55], v[200:201]
	s_and_b64 vcc, exec, s[46:47]
	v_mov_b32_e32 v60, v200
	v_mov_b32_e32 v61, v200
	v_pk_mul_f32 v[56:57], v[56:57], v[60:61]
	v_pk_mul_f32 v[52:53], v[52:53], v[60:61]
	v_pk_mul_f32 v[50:51], v[50:51], v[200:201]
	s_cbranch_vccnz .LBB0_573
	v_and_b32_e32 v61, 64, v226
	v_xor_b32_e32 v60, 16, v226
	v_add_u32_e32 v61, 64, v61
	v_cmp_lt_i32_e32 vcc, v60, v61
	s_nop 1
	v_cndmask_b32_e32 v60, v226, v60, vcc
	v_lshlrev_b32_e32 v64, 2, v60
	ds_bpermute_b32 v63, v64, v54
	ds_bpermute_b32 v61, v64, v50
	v_cmp_lt_i32_e32 vcc, 0, v233
	s_and_saveexec_b64 s[4:5], vcc
	s_xor_b64 s[4:5], exec, s[4:5]
	s_cbranch_execz .LBB0_552
	v_cmp_eq_u32_e32 vcc, 1, v233
	s_and_saveexec_b64 s[6:7], vcc
	s_cbranch_execz .LBB0_551
	v_mov_b32_e32 v66, v54
	v_mov_b32_e32 v67, v154
	v_mov_b32_e32 v62, v158
	s_waitcnt lgkmcnt(0)
	v_pk_mul_f32 v[62:63], v[66:67], v[62:63]
	v_mov_b32_e32 v66, v50
	v_mov_b32_e32 v67, v146
	v_mov_b32_e32 v60, v150
	v_pk_mul_f32 v[60:61], v[66:67], v[60:61]
	v_add_f32_e32 v54, v62, v63
	v_add_f32_e32 v50, v60, v61

.LBB0_552:
	s_andn2_saveexec_b64 s[4:5], s[4:5]
	s_cbranch_execz .LBB0_554
	v_mov_b32_e32 v66, v54
	v_mov_b32_e32 v67, v154
	v_mov_b32_e32 v62, v158
	s_waitcnt lgkmcnt(0)
	v_pk_mul_f32 v[62:63], v[66:67], v[62:63]
	v_mov_b32_e32 v66, v50
	v_mov_b32_e32 v67, v146
	v_mov_b32_e32 v60, v150
	v_pk_mul_f32 v[60:61], v[66:67], v[60:61]
	v_sub_f32_e32 v54, v62, v63
	v_sub_f32_e32 v50, v60, v61
.LBB0_554:
	s_or_b64 exec, exec, s[4:5]
	s_waitcnt lgkmcnt(0)
	ds_bpermute_b32 v63, v64, v55
	ds_bpermute_b32 v61, v64, v51
	v_cmp_lt_i32_e32 vcc, 0, v233
	s_and_saveexec_b64 s[4:5], vcc
	s_xor_b64 s[4:5], exec, s[4:5]
	s_cbranch_execz .LBB0_558
	v_cmp_eq_u32_e32 vcc, 1, v233
	s_and_saveexec_b64 s[6:7], vcc
	s_cbranch_execz .LBB0_557
	v_mov_b32_e32 v154, v159
	v_mov_b32_e32 v62, v55
	v_mul_f32_e32 v60, v159, v55
	s_waitcnt lgkmcnt(0)
	v_pk_fma_f32 v[62:63], v[154:155], v[62:63], v[60:61] op_sel_hi:[1,1,0]
	v_mov_b32_e32 v146, v151
	v_mov_b32_e32 v60, v51
	v_mul_f32_e32 v62, v151, v51
	v_pk_fma_f32 v[60:61], v[146:147], v[60:61], v[62:63] op_sel_hi:[1,1,0]
	v_mov_b32_e32 v55, v63
	v_mov_b32_e32 v51, v61

.LBB0_558:
	s_andn2_saveexec_b64 s[4:5], s[4:5]
	s_cbranch_execz .LBB0_560
	v_mov_b32_e32 v154, v159
	v_mov_b32_e32 v62, v55
	v_mul_f32_e32 v60, v159, v55
	s_waitcnt lgkmcnt(0)
	v_pk_fma_f32 v[62:63], v[154:155], v[62:63], v[60:61] op_sel_hi:[1,1,0] neg_lo:[1,0,0] neg_hi:[1,0,0]
	v_mov_b32_e32 v146, v151
	v_mov_b32_e32 v60, v51
	v_mul_f32_e32 v62, v151, v51
	v_pk_fma_f32 v[60:61], v[146:147], v[60:61], v[62:63] op_sel_hi:[1,1,0] neg_lo:[1,0,0] neg_hi:[1,0,0]
	v_mov_b32_e32 v55, v63
	v_mov_b32_e32 v51, v61
.LBB0_560:
	s_or_b64 exec, exec, s[4:5]
	s_waitcnt lgkmcnt(0)
	ds_bpermute_b32 v63, v64, v56
	ds_bpermute_b32 v61, v64, v52
	v_cmp_lt_i32_e32 vcc, 0, v233
	s_and_saveexec_b64 s[4:5], vcc
	s_xor_b64 s[4:5], exec, s[4:5]
	s_cbranch_execz .LBB0_564
	v_cmp_eq_u32_e32 vcc, 1, v233
	s_and_saveexec_b64 s[6:7], vcc
	s_cbranch_execz .LBB0_563
	v_mov_b32_e32 v66, v160
	v_mov_b32_e32 v67, v156
	v_mov_b32_e32 v62, v56
	s_waitcnt lgkmcnt(1)
	v_mul_f32_e32 v56, v156, v63
	v_pk_fma_f32 v[62:63], v[66:67], v[62:63], v[56:57] op_sel_hi:[1,1,0]
	v_mov_b32_e32 v66, v152
	v_mov_b32_e32 v67, v148
	v_mov_b32_e32 v60, v52
	s_waitcnt lgkmcnt(0)
	v_mul_f32_e32 v52, v148, v61
	v_pk_fma_f32 v[60:61], v[66:67], v[60:61], v[52:53] op_sel_hi:[1,1,0]
	v_mov_b32_e32 v56, v62
	v_mov_b32_e32 v52, v60

.LBB0_564:
	s_andn2_saveexec_b64 s[4:5], s[4:5]
	s_cbranch_execz .LBB0_566
	v_mov_b32_e32 v66, v160
	v_mov_b32_e32 v67, v156
	v_mov_b32_e32 v62, v56
	s_waitcnt lgkmcnt(1)
	v_mul_f32_e32 v56, v156, v63
	v_pk_fma_f32 v[62:63], v[66:67], v[62:63], v[56:57] op_sel_hi:[1,1,0] neg_lo:[0,0,1] neg_hi:[0,0,1]
	v_mov_b32_e32 v66, v152
	v_mov_b32_e32 v67, v148
	v_mov_b32_e32 v60, v52
	s_waitcnt lgkmcnt(0)
	v_mul_f32_e32 v52, v148, v61
	v_pk_fma_f32 v[60:61], v[66:67], v[60:61], v[52:53] op_sel_hi:[1,1,0] neg_lo:[0,0,1] neg_hi:[0,0,1]
	v_mov_b32_e32 v56, v62
	v_mov_b32_e32 v52, v60
.LBB0_566:
	s_or_b64 exec, exec, s[4:5]
	s_waitcnt lgkmcnt(0)
	ds_bpermute_b32 v63, v64, v57
	ds_bpermute_b32 v61, v64, v53
	v_cmp_lt_i32_e32 vcc, 0, v233
	s_and_saveexec_b64 s[4:5], vcc
	s_xor_b64 s[4:5], exec, s[4:5]
	s_cbranch_execz .LBB0_570
	v_cmp_eq_u32_e32 vcc, 1, v233
	s_and_saveexec_b64 s[6:7], vcc
	s_cbranch_execz .LBB0_569
	v_mov_b32_e32 v156, v161
	v_mov_b32_e32 v62, v57
	s_waitcnt lgkmcnt(1)
	v_mul_f32_e32 v60, v157, v63
	s_waitcnt lgkmcnt(0)
	v_pk_fma_f32 v[62:63], v[156:157], v[62:63], v[60:61] op_sel_hi:[1,1,0]
	v_mov_b32_e32 v148, v153
	v_mov_b32_e32 v60, v53
	v_mul_f32_e32 v64, v149, v61
	v_pk_fma_f32 v[60:61], v[148:149], v[60:61], v[64:65] op_sel_hi:[1,1,0]
	v_mov_b32_e32 v57, v62
	v_mov_b32_e32 v53, v60

.LBB0_570:
	s_andn2_saveexec_b64 s[4:5], s[4:5]
	s_cbranch_execz .LBB0_572
	v_mov_b32_e32 v156, v161
	v_mov_b32_e32 v62, v57
	s_waitcnt lgkmcnt(1)
	v_mul_f32_e32 v60, v157, v63
	s_waitcnt lgkmcnt(0)
	v_pk_fma_f32 v[62:63], v[156:157], v[62:63], v[60:61] op_sel_hi:[1,1,0] neg_lo:[0,0,1] neg_hi:[0,0,1]
	v_mov_b32_e32 v148, v153
	v_mov_b32_e32 v60, v53
	v_mul_f32_e32 v64, v149, v61
	v_pk_fma_f32 v[60:61], v[148:149], v[60:61], v[64:65] op_sel_hi:[1,1,0] neg_lo:[0,0,1] neg_hi:[0,0,1]
	v_mov_b32_e32 v57, v62
	v_mov_b32_e32 v53, v60

.LBB0_573:
	s_waitcnt lgkmcnt(0)
	v_pk_mul_f32 v[60:61], v[54:55], s[36:37] op_sel_hi:[1,0]
	v_pk_mul_f32 v[64:65], v[50:51], s[36:37] op_sel_hi:[1,0]
	v_pk_mul_f32 v[66:67], v[52:53], s[36:37] op_sel_hi:[1,0]
	v_cndmask_b32_e64 v54, v54, v60, s[44:45]
	v_cndmask_b32_e64 v55, v55, v61, s[44:45]
	v_cndmask_b32_e64 v60, v52, v66, s[44:45]
	v_cndmask_b32_e64 v52, v50, v64, s[44:45]
	v_cvt_pk_bf16_f32 v50, v54, v55
	v_lshl_add_u64 v[54:55], v[214:215], 1, v[58:59]
	s_movk_i32 s4, 0xf100
	v_add_co_u32_e32 v54, vcc, s4, v54
	v_pk_mul_f32 v[62:63], v[56:57], s[36:37] op_sel_hi:[1,0]
	s_nop 0
	v_addc_co_u32_e32 v55, vcc, -1, v55, vcc
	v_cndmask_b32_e64 v53, v53, v67, s[44:45]
	v_pk_mul_f32 v[48:49], v[48:49], v[196:197] op_sel_hi:[1,0]
	v_pk_mul_f32 v[46:47], v[46:47], v[196:197] op_sel_hi:[1,0]
	v_pk_mul_f32 v[44:45], v[44:45], v[196:197] op_sel_hi:[1,0]
	s_and_b64 vcc, exec, s[42:43]
	v_pk_mul_f32 v[42:43], v[42:43], v[196:197] op_sel_hi:[1,0]
	v_cndmask_b32_e64 v56, v56, v62, s[44:45]
	v_cndmask_b32_e64 v57, v57, v63, s[44:45]
	v_cndmask_b32_e64 v61, v51, v65, s[44:45]
	v_cvt_pk_bf16_f32 v51, v56, v57
	v_cvt_pk_bf16_f32 v52, v52, v61
	v_cvt_pk_bf16_f32 v53, v60, v53
	flat_store_dwordx4 v[54:55], v[50:53] nt
	s_cbranch_vccnz .LBB0_599
	s_nop 0
	v_and_b32_e32 v51, 64, v226
	v_xor_b32_e32 v50, 16, v226
	v_add_u32_e32 v51, 64, v51
	v_cmp_lt_i32_e32 vcc, v50, v51
	s_nop 1
	v_cndmask_b32_e32 v50, v226, v50, vcc
	v_lshlrev_b32_e32 v54, 2, v50
	ds_bpermute_b32 v53, v54, v46
	ds_bpermute_b32 v51, v54, v42
	v_cmp_lt_i32_e32 vcc, 0, v233
	s_and_saveexec_b64 s[4:5], vcc
	s_xor_b64 s[4:5], exec, s[4:5]
	s_cbranch_execz .LBB0_578
	v_cmp_eq_u32_e32 vcc, 1, v233
	s_and_saveexec_b64 s[6:7], vcc
	s_cbranch_execz .LBB0_577
	v_mov_b32_e32 v56, v46
	v_mov_b32_e32 v57, v138
	v_mov_b32_e32 v52, v142
	s_waitcnt lgkmcnt(0)
	v_pk_mul_f32 v[52:53], v[56:57], v[52:53]
	v_mov_b32_e32 v56, v42
	v_mov_b32_e32 v57, v130
	v_mov_b32_e32 v50, v134
	v_pk_mul_f32 v[50:51], v[56:57], v[50:51]
	v_add_f32_e32 v46, v52, v53
	v_add_f32_e32 v42, v50, v51

.LBB0_578:
	s_andn2_saveexec_b64 s[4:5], s[4:5]
	s_cbranch_execz .LBB0_580
	v_mov_b32_e32 v56, v46
	v_mov_b32_e32 v57, v138
	v_mov_b32_e32 v52, v142
	s_waitcnt lgkmcnt(0)
	v_pk_mul_f32 v[52:53], v[56:57], v[52:53]
	v_mov_b32_e32 v56, v42
	v_mov_b32_e32 v57, v130
	v_mov_b32_e32 v50, v134
	v_pk_mul_f32 v[50:51], v[56:57], v[50:51]
	v_sub_f32_e32 v46, v52, v53
	v_sub_f32_e32 v42, v50, v51
.LBB0_580:
	s_or_b64 exec, exec, s[4:5]
	s_waitcnt lgkmcnt(0)
	ds_bpermute_b32 v53, v54, v47
	ds_bpermute_b32 v51, v54, v43
	v_cmp_lt_i32_e32 vcc, 0, v233
	s_and_saveexec_b64 s[4:5], vcc
	s_xor_b64 s[4:5], exec, s[4:5]
	s_cbranch_execz .LBB0_584
	v_cmp_eq_u32_e32 vcc, 1, v233
	s_and_saveexec_b64 s[6:7], vcc
	s_cbranch_execz .LBB0_583
	v_mov_b32_e32 v56, v143
	v_mov_b32_e32 v57, v139
	v_mov_b32_e32 v52, v47
	v_mul_f32_e32 v50, v143, v47
	s_waitcnt lgkmcnt(0)
	v_pk_fma_f32 v[52:53], v[56:57], v[52:53], v[50:51] op_sel_hi:[1,1,0]
	v_mov_b32_e32 v56, v135
	v_mov_b32_e32 v57, v131
	v_mov_b32_e32 v50, v43
	v_mul_f32_e32 v52, v135, v43
	v_pk_fma_f32 v[50:51], v[56:57], v[50:51], v[52:53] op_sel_hi:[1,1,0]
	v_mov_b32_e32 v47, v53
	v_mov_b32_e32 v43, v51

.LBB0_584:
	s_andn2_saveexec_b64 s[4:5], s[4:5]
	s_cbranch_execz .LBB0_586
	v_mov_b32_e32 v56, v143
	v_mov_b32_e32 v57, v139
	v_mov_b32_e32 v52, v47
	v_mul_f32_e32 v50, v143, v47
	s_waitcnt lgkmcnt(0)
	v_pk_fma_f32 v[52:53], v[56:57], v[52:53], v[50:51] op_sel_hi:[1,1,0] neg_lo:[1,0,0] neg_hi:[1,0,0]
	v_mov_b32_e32 v56, v135
	v_mov_b32_e32 v57, v131
	v_mov_b32_e32 v50, v43
	v_mul_f32_e32 v52, v135, v43
	v_pk_fma_f32 v[50:51], v[56:57], v[50:51], v[52:53] op_sel_hi:[1,1,0] neg_lo:[1,0,0] neg_hi:[1,0,0]
	v_mov_b32_e32 v47, v53
	v_mov_b32_e32 v43, v51
.LBB0_586:
	s_or_b64 exec, exec, s[4:5]
	s_waitcnt lgkmcnt(0)
	ds_bpermute_b32 v53, v54, v48
	ds_bpermute_b32 v51, v54, v44
	v_cmp_lt_i32_e32 vcc, 0, v233
	s_and_saveexec_b64 s[4:5], vcc
	s_xor_b64 s[4:5], exec, s[4:5]
	s_cbranch_execz .LBB0_590
	v_cmp_eq_u32_e32 vcc, 1, v233
	s_and_saveexec_b64 s[6:7], vcc
	s_cbranch_execz .LBB0_589
	v_mov_b32_e32 v56, v144
	v_mov_b32_e32 v57, v140
	v_mov_b32_e32 v52, v48
	s_waitcnt lgkmcnt(1)
	v_mul_f32_e32 v48, v140, v53
	v_pk_fma_f32 v[52:53], v[56:57], v[52:53], v[48:49] op_sel_hi:[1,1,0]
	v_mov_b32_e32 v56, v136
	v_mov_b32_e32 v57, v132
	v_mov_b32_e32 v50, v44
	s_waitcnt lgkmcnt(0)
	v_mul_f32_e32 v44, v132, v51
	v_pk_fma_f32 v[50:51], v[56:57], v[50:51], v[44:45] op_sel_hi:[1,1,0]
	v_mov_b32_e32 v48, v52
	v_mov_b32_e32 v44, v50

.LBB0_590:
	s_andn2_saveexec_b64 s[4:5], s[4:5]
	s_cbranch_execz .LBB0_592
	v_mov_b32_e32 v56, v144
	v_mov_b32_e32 v57, v140
	v_mov_b32_e32 v52, v48
	s_waitcnt lgkmcnt(1)
	v_mul_f32_e32 v48, v140, v53
	v_pk_fma_f32 v[52:53], v[56:57], v[52:53], v[48:49] op_sel_hi:[1,1,0] neg_lo:[0,0,1] neg_hi:[0,0,1]
	v_mov_b32_e32 v56, v136
	v_mov_b32_e32 v57, v132
	v_mov_b32_e32 v50, v44
	s_waitcnt lgkmcnt(0)
	v_mul_f32_e32 v44, v132, v51
	v_pk_fma_f32 v[50:51], v[56:57], v[50:51], v[44:45] op_sel_hi:[1,1,0] neg_lo:[0,0,1] neg_hi:[0,0,1]
	v_mov_b32_e32 v48, v52
	v_mov_b32_e32 v44, v50
.LBB0_592:
	s_or_b64 exec, exec, s[4:5]
	s_waitcnt lgkmcnt(0)
	ds_bpermute_b32 v53, v54, v49
	ds_bpermute_b32 v51, v54, v45
	v_cmp_lt_i32_e32 vcc, 0, v233
	s_and_saveexec_b64 s[4:5], vcc
	s_xor_b64 s[4:5], exec, s[4:5]
	s_cbranch_execz .LBB0_596
	v_cmp_eq_u32_e32 vcc, 1, v233
	s_and_saveexec_b64 s[6:7], vcc
	s_cbranch_execz .LBB0_595
	v_mov_b32_e32 v54, v145
	v_mov_b32_e32 v55, v141
	v_mov_b32_e32 v52, v49
	s_waitcnt lgkmcnt(1)
	v_mul_f32_e32 v50, v141, v53
	s_waitcnt lgkmcnt(0)
	v_pk_fma_f32 v[52:53], v[54:55], v[52:53], v[50:51] op_sel_hi:[1,1,0]
	v_mov_b32_e32 v54, v137
	v_mov_b32_e32 v55, v133
	v_mov_b32_e32 v50, v45
	v_mul_f32_e32 v56, v133, v51
	v_pk_fma_f32 v[50:51], v[54:55], v[50:51], v[56:57] op_sel_hi:[1,1,0]
	v_mov_b32_e32 v49, v52
	v_mov_b32_e32 v45, v50

.LBB0_596:
	s_andn2_saveexec_b64 s[4:5], s[4:5]
	s_cbranch_execz .LBB0_598
	v_mov_b32_e32 v54, v145
	v_mov_b32_e32 v55, v141
	v_mov_b32_e32 v52, v49
	s_waitcnt lgkmcnt(1)
	v_mul_f32_e32 v50, v141, v53
	s_waitcnt lgkmcnt(0)
	v_pk_fma_f32 v[52:53], v[54:55], v[52:53], v[50:51] op_sel_hi:[1,1,0] neg_lo:[0,0,1] neg_hi:[0,0,1]
	v_mov_b32_e32 v54, v137
	v_mov_b32_e32 v55, v133
	v_mov_b32_e32 v50, v45
	v_mul_f32_e32 v56, v133, v51
	v_pk_fma_f32 v[50:51], v[54:55], v[50:51], v[56:57] op_sel_hi:[1,1,0] neg_lo:[0,0,1] neg_hi:[0,0,1]
	v_mov_b32_e32 v49, v52
	v_mov_b32_e32 v45, v50

.LBB0_599:
	s_waitcnt lgkmcnt(0)
	v_pk_mul_f32 v[50:51], v[46:47], s[36:37] op_sel_hi:[1,0]
	v_pk_mul_f32 v[54:55], v[42:43], s[36:37] op_sel_hi:[1,0]
	v_pk_mul_f32 v[52:53], v[48:49], s[36:37] op_sel_hi:[1,0]
	v_pk_mul_f32 v[56:57], v[44:45], s[36:37] op_sel_hi:[1,0]
	v_cndmask_b32_e64 v46, v46, v50, s[40:41]
	v_cndmask_b32_e64 v42, v42, v54, s[40:41]
	v_cndmask_b32_e64 v43, v43, v55, s[40:41]
	v_cndmask_b32_e64 v48, v48, v52, s[40:41]
	v_cndmask_b32_e64 v49, v49, v53, s[40:41]
	v_cndmask_b32_e64 v47, v47, v51, s[40:41]
	v_cndmask_b32_e64 v50, v44, v56, s[40:41]
	v_cndmask_b32_e64 v51, v45, v57, s[40:41]
	v_cvt_pk_bf16_f32 v44, v46, v47
	v_cvt_pk_bf16_f32 v45, v48, v49
	v_cvt_pk_bf16_f32 v46, v42, v43
	v_mov_b64_e32 v[42:43], s[62:63]
	s_movk_i32 s4, 0x1200
	v_mad_i64_i32 v[42:43], s[4:5], v194, s4, v[42:43]
	v_lshl_add_u64 v[48:49], v[0:1], 1, v[42:43]
	s_movk_i32 s4, 0xf000
	v_add_co_u32_e32 v48, vcc, s4, v48
	v_mov_b32_e32 v197, v196
	s_nop 0
	v_addc_co_u32_e32 v49, vcc, -1, v49, vcc
	v_cvt_pk_bf16_f32 v47, v50, v51
	flat_store_dwordx4 v[48:49], v[44:47] nt
	v_pk_mul_f32 v[38:39], v[38:39], v[196:197]
	s_and_b64 vcc, exec, s[46:47]
	v_mov_b32_e32 v44, v196
	v_mov_b32_e32 v45, v196
	v_pk_mul_f32 v[40:41], v[40:41], v[44:45]
	v_pk_mul_f32 v[36:37], v[36:37], v[44:45]
	v_pk_mul_f32 v[34:35], v[34:35], v[196:197]
	s_cbranch_vccnz .LBB0_625
	v_and_b32_e32 v45, 64, v226
	v_xor_b32_e32 v44, 16, v226
	v_add_u32_e32 v45, 64, v45
	v_cmp_lt_i32_e32 vcc, v44, v45
	s_nop 1
	v_cndmask_b32_e32 v44, v226, v44, vcc
	v_lshlrev_b32_e32 v48, 2, v44
	ds_bpermute_b32 v47, v48, v38
	ds_bpermute_b32 v45, v48, v34
	v_cmp_lt_i32_e32 vcc, 0, v233
	s_and_saveexec_b64 s[4:5], vcc
	s_xor_b64 s[4:5], exec, s[4:5]
	s_cbranch_execz .LBB0_604
	v_cmp_eq_u32_e32 vcc, 1, v233
	s_and_saveexec_b64 s[6:7], vcc
	s_cbranch_execz .LBB0_603
	v_mov_b32_e32 v50, v38
	v_mov_b32_e32 v51, v138
	v_mov_b32_e32 v46, v142
	s_waitcnt lgkmcnt(0)
	v_pk_mul_f32 v[46:47], v[50:51], v[46:47]
	v_mov_b32_e32 v50, v34
	v_mov_b32_e32 v51, v130
	v_mov_b32_e32 v44, v134
	v_pk_mul_f32 v[44:45], v[50:51], v[44:45]
	v_add_f32_e32 v38, v46, v47
	v_add_f32_e32 v34, v44, v45

.LBB0_604:
	s_andn2_saveexec_b64 s[4:5], s[4:5]
	s_cbranch_execz .LBB0_606
	v_mov_b32_e32 v50, v38
	v_mov_b32_e32 v51, v138
	v_mov_b32_e32 v46, v142
	s_waitcnt lgkmcnt(0)
	v_pk_mul_f32 v[46:47], v[50:51], v[46:47]
	v_mov_b32_e32 v50, v34
	v_mov_b32_e32 v51, v130
	v_mov_b32_e32 v44, v134
	v_pk_mul_f32 v[44:45], v[50:51], v[44:45]
	v_sub_f32_e32 v38, v46, v47
	v_sub_f32_e32 v34, v44, v45
.LBB0_606:
	s_or_b64 exec, exec, s[4:5]
	s_waitcnt lgkmcnt(0)
	ds_bpermute_b32 v47, v48, v39
	ds_bpermute_b32 v45, v48, v35
	v_cmp_lt_i32_e32 vcc, 0, v233
	s_and_saveexec_b64 s[4:5], vcc
	s_xor_b64 s[4:5], exec, s[4:5]
	s_cbranch_execz .LBB0_610
	v_cmp_eq_u32_e32 vcc, 1, v233
	s_and_saveexec_b64 s[6:7], vcc
	s_cbranch_execz .LBB0_609
	v_mov_b32_e32 v138, v143
	v_mov_b32_e32 v46, v39
	v_mul_f32_e32 v44, v143, v39
	s_waitcnt lgkmcnt(0)
	v_pk_fma_f32 v[46:47], v[138:139], v[46:47], v[44:45] op_sel_hi:[1,1,0]
	v_mov_b32_e32 v130, v135
	v_mov_b32_e32 v44, v35
	v_mul_f32_e32 v46, v135, v35
	v_pk_fma_f32 v[44:45], v[130:131], v[44:45], v[46:47] op_sel_hi:[1,1,0]
	v_mov_b32_e32 v39, v47
	v_mov_b32_e32 v35, v45

.LBB0_610:
	s_andn2_saveexec_b64 s[4:5], s[4:5]
	s_cbranch_execz .LBB0_612
	v_mov_b32_e32 v138, v143
	v_mov_b32_e32 v46, v39
	v_mul_f32_e32 v44, v143, v39
	s_waitcnt lgkmcnt(0)
	v_pk_fma_f32 v[46:47], v[138:139], v[46:47], v[44:45] op_sel_hi:[1,1,0] neg_lo:[1,0,0] neg_hi:[1,0,0]
	v_mov_b32_e32 v130, v135
	v_mov_b32_e32 v44, v35
	v_mul_f32_e32 v46, v135, v35
	v_pk_fma_f32 v[44:45], v[130:131], v[44:45], v[46:47] op_sel_hi:[1,1,0] neg_lo:[1,0,0] neg_hi:[1,0,0]
	v_mov_b32_e32 v39, v47
	v_mov_b32_e32 v35, v45
.LBB0_612:
	s_or_b64 exec, exec, s[4:5]
	s_waitcnt lgkmcnt(0)
	ds_bpermute_b32 v47, v48, v40
	ds_bpermute_b32 v45, v48, v36
	v_cmp_lt_i32_e32 vcc, 0, v233
	s_and_saveexec_b64 s[4:5], vcc
	s_xor_b64 s[4:5], exec, s[4:5]
	s_cbranch_execz .LBB0_616
	v_cmp_eq_u32_e32 vcc, 1, v233
	s_and_saveexec_b64 s[6:7], vcc
	s_cbranch_execz .LBB0_615
	v_mov_b32_e32 v50, v144
	v_mov_b32_e32 v51, v140
	v_mov_b32_e32 v46, v40
	s_waitcnt lgkmcnt(1)
	v_mul_f32_e32 v40, v140, v47
	v_pk_fma_f32 v[46:47], v[50:51], v[46:47], v[40:41] op_sel_hi:[1,1,0]
	v_mov_b32_e32 v50, v136
	v_mov_b32_e32 v51, v132
	v_mov_b32_e32 v44, v36
	s_waitcnt lgkmcnt(0)
	v_mul_f32_e32 v36, v132, v45
	v_pk_fma_f32 v[44:45], v[50:51], v[44:45], v[36:37] op_sel_hi:[1,1,0]
	v_mov_b32_e32 v40, v46
	v_mov_b32_e32 v36, v44

.LBB0_616:
	s_andn2_saveexec_b64 s[4:5], s[4:5]
	s_cbranch_execz .LBB0_618
	v_mov_b32_e32 v50, v144
	v_mov_b32_e32 v51, v140
	v_mov_b32_e32 v46, v40
	s_waitcnt lgkmcnt(1)
	v_mul_f32_e32 v40, v140, v47
	v_pk_fma_f32 v[46:47], v[50:51], v[46:47], v[40:41] op_sel_hi:[1,1,0] neg_lo:[0,0,1] neg_hi:[0,0,1]
	v_mov_b32_e32 v50, v136
	v_mov_b32_e32 v51, v132
	v_mov_b32_e32 v44, v36
	s_waitcnt lgkmcnt(0)
	v_mul_f32_e32 v36, v132, v45
	v_pk_fma_f32 v[44:45], v[50:51], v[44:45], v[36:37] op_sel_hi:[1,1,0] neg_lo:[0,0,1] neg_hi:[0,0,1]
	v_mov_b32_e32 v40, v46
	v_mov_b32_e32 v36, v44
.LBB0_618:
	s_or_b64 exec, exec, s[4:5]
	s_waitcnt lgkmcnt(0)
	ds_bpermute_b32 v47, v48, v41
	ds_bpermute_b32 v45, v48, v37
	v_cmp_lt_i32_e32 vcc, 0, v233
	s_and_saveexec_b64 s[4:5], vcc
	s_xor_b64 s[4:5], exec, s[4:5]
	s_cbranch_execz .LBB0_622
	v_cmp_eq_u32_e32 vcc, 1, v233
	s_and_saveexec_b64 s[6:7], vcc
	s_cbranch_execz .LBB0_621
	v_mov_b32_e32 v140, v145
	v_mov_b32_e32 v46, v41
	s_waitcnt lgkmcnt(1)
	v_mul_f32_e32 v44, v141, v47
	s_waitcnt lgkmcnt(0)
	v_pk_fma_f32 v[46:47], v[140:141], v[46:47], v[44:45] op_sel_hi:[1,1,0]
	v_mov_b32_e32 v132, v137
	v_mov_b32_e32 v44, v37
	v_mul_f32_e32 v48, v133, v45
	v_pk_fma_f32 v[44:45], v[132:133], v[44:45], v[48:49] op_sel_hi:[1,1,0]
	v_mov_b32_e32 v41, v46
	v_mov_b32_e32 v37, v44

.LBB0_622:
	s_andn2_saveexec_b64 s[4:5], s[4:5]
	s_cbranch_execz .LBB0_624
	v_mov_b32_e32 v140, v145
	v_mov_b32_e32 v46, v41
	s_waitcnt lgkmcnt(1)
	v_mul_f32_e32 v44, v141, v47
	s_waitcnt lgkmcnt(0)
	v_pk_fma_f32 v[46:47], v[140:141], v[46:47], v[44:45] op_sel_hi:[1,1,0] neg_lo:[0,0,1] neg_hi:[0,0,1]
	v_mov_b32_e32 v132, v137
	v_mov_b32_e32 v44, v37
	v_mul_f32_e32 v48, v133, v45
	v_pk_fma_f32 v[44:45], v[132:133], v[44:45], v[48:49] op_sel_hi:[1,1,0] neg_lo:[0,0,1] neg_hi:[0,0,1]
	v_mov_b32_e32 v41, v46
	v_mov_b32_e32 v37, v44

.LBB0_625:
	s_waitcnt lgkmcnt(0)
	v_pk_mul_f32 v[44:45], v[38:39], s[36:37] op_sel_hi:[1,0]
	v_pk_mul_f32 v[48:49], v[34:35], s[36:37] op_sel_hi:[1,0]
	v_pk_mul_f32 v[50:51], v[36:37], s[36:37] op_sel_hi:[1,0]
	v_cndmask_b32_e64 v38, v38, v44, s[44:45]
	v_cndmask_b32_e64 v39, v39, v45, s[44:45]
	v_cndmask_b32_e64 v44, v36, v50, s[44:45]
	v_cndmask_b32_e64 v36, v34, v48, s[44:45]
	v_cvt_pk_bf16_f32 v34, v38, v39
	v_lshl_add_u64 v[38:39], v[214:215], 1, v[42:43]
	v_add_co_u32_e32 v38, vcc, 0xfffff100, v38
	v_pk_mul_f32 v[46:47], v[40:41], s[36:37] op_sel_hi:[1,0]
	s_nop 0
	v_addc_co_u32_e32 v39, vcc, -1, v39, vcc
	v_cndmask_b32_e64 v37, v37, v51, s[44:45]
	s_and_b64 vcc, exec, s[48:49]
	v_cndmask_b32_e64 v40, v40, v46, s[44:45]
	v_cndmask_b32_e64 v41, v41, v47, s[44:45]
	v_cndmask_b32_e64 v45, v35, v49, s[44:45]
	v_cvt_pk_bf16_f32 v35, v40, v41
	v_cvt_pk_bf16_f32 v36, v36, v45
	v_cvt_pk_bf16_f32 v37, v44, v37
	flat_store_dwordx4 v[38:39], v[34:37] nt
	s_cbranch_vccnz .LBB0_627
	s_nop 0
	v_lshlrev_b64 v[34:35], 6, v[190:191]
	v_lshl_add_u64 v[34:35], s[64:65], 0, v[34:35]
	flat_load_dwordx4 v[126:129], v[34:35]
	flat_load_dwordx4 v[118:121], v[34:35] offset:16
	flat_load_dwordx4 v[122:125], v[34:35] offset:32
	flat_load_dwordx4 v[114:117], v[34:35] offset:48
	v_lshlrev_b64 v[34:35], 6, v[174:175]
	v_lshl_add_u64 v[34:35], s[64:65], 0, v[34:35]
	flat_load_dwordx4 v[110:113], v[34:35]
	flat_load_dwordx4 v[102:105], v[34:35] offset:16
	flat_load_dwordx4 v[106:109], v[34:35] offset:32
	flat_load_dwordx4 v[98:101], v[34:35] offset:48
.LBB0_627:
	s_waitcnt vmcnt(0)
	v_pk_mul_f32 v[32:33], v[32:33], v[192:193] op_sel_hi:[1,0]
	v_pk_mul_f32 v[30:31], v[30:31], v[192:193] op_sel_hi:[1,0]
	v_pk_mul_f32 v[28:29], v[28:29], v[192:193] op_sel_hi:[1,0]
	s_and_b64 vcc, exec, s[42:43]
	v_pk_mul_f32 v[26:27], v[26:27], v[192:193] op_sel_hi:[1,0]
	s_cbranch_vccnz .LBB0_653
	v_and_b32_e32 v35, 64, v226
	v_xor_b32_e32 v34, 16, v226
	v_add_u32_e32 v35, 64, v35
	v_cmp_lt_i32_e32 vcc, v34, v35
	s_nop 1
	v_cndmask_b32_e32 v34, v226, v34, vcc
	v_lshlrev_b32_e32 v38, 2, v34
	ds_bpermute_b32 v37, v38, v30
	ds_bpermute_b32 v35, v38, v26
	v_cmp_lt_i32_e32 vcc, 0, v233
	s_and_saveexec_b64 s[4:5], vcc
	s_xor_b64 s[4:5], exec, s[4:5]
	s_cbranch_execz .LBB0_632
	v_cmp_eq_u32_e32 vcc, 1, v233
	s_and_saveexec_b64 s[6:7], vcc
	s_cbranch_execz .LBB0_631
	v_mov_b32_e32 v40, v30
	s_waitcnt lgkmcnt(0)
	v_mov_b32_e32 v41, v122
	v_mov_b32_e32 v36, v126
	v_pk_mul_f32 v[36:37], v[40:41], v[36:37]
	v_mov_b32_e32 v40, v26
	v_mov_b32_e32 v41, v114
	v_mov_b32_e32 v34, v118
	v_pk_mul_f32 v[34:35], v[40:41], v[34:35]
	v_add_f32_e32 v30, v36, v37
	v_add_f32_e32 v26, v34, v35

.LBB0_632:
	s_andn2_saveexec_b64 s[4:5], s[4:5]
	s_cbranch_execz .LBB0_634
	v_mov_b32_e32 v40, v30
	s_waitcnt lgkmcnt(0)
	v_mov_b32_e32 v41, v122
	v_mov_b32_e32 v36, v126
	v_pk_mul_f32 v[36:37], v[40:41], v[36:37]
	v_mov_b32_e32 v40, v26
	v_mov_b32_e32 v41, v114
	v_mov_b32_e32 v34, v118
	v_pk_mul_f32 v[34:35], v[40:41], v[34:35]
	v_sub_f32_e32 v30, v36, v37
	v_sub_f32_e32 v26, v34, v35
.LBB0_634:
	s_or_b64 exec, exec, s[4:5]
	s_waitcnt lgkmcnt(0)
	ds_bpermute_b32 v37, v38, v31
	ds_bpermute_b32 v35, v38, v27
	v_cmp_lt_i32_e32 vcc, 0, v233
	s_and_saveexec_b64 s[4:5], vcc
	s_xor_b64 s[4:5], exec, s[4:5]
	s_cbranch_execz .LBB0_638
	v_cmp_eq_u32_e32 vcc, 1, v233
	s_and_saveexec_b64 s[6:7], vcc
	s_cbranch_execz .LBB0_637
	v_mov_b32_e32 v40, v127
	v_mov_b32_e32 v41, v123
	v_mov_b32_e32 v36, v31
	v_mul_f32_e32 v34, v127, v31
	s_waitcnt lgkmcnt(0)
	v_pk_fma_f32 v[36:37], v[40:41], v[36:37], v[34:35] op_sel_hi:[1,1,0]
	v_mov_b32_e32 v40, v119
	v_mov_b32_e32 v41, v115
	v_mov_b32_e32 v34, v27
	v_mul_f32_e32 v36, v119, v27
	v_pk_fma_f32 v[34:35], v[40:41], v[34:35], v[36:37] op_sel_hi:[1,1,0]
	v_mov_b32_e32 v31, v37
	v_mov_b32_e32 v27, v35

.LBB0_638:
	s_andn2_saveexec_b64 s[4:5], s[4:5]
	s_cbranch_execz .LBB0_640
	v_mov_b32_e32 v40, v127
	v_mov_b32_e32 v41, v123
	v_mov_b32_e32 v36, v31
	v_mul_f32_e32 v34, v127, v31
	s_waitcnt lgkmcnt(0)
	v_pk_fma_f32 v[36:37], v[40:41], v[36:37], v[34:35] op_sel_hi:[1,1,0] neg_lo:[1,0,0] neg_hi:[1,0,0]
	v_mov_b32_e32 v40, v119
	v_mov_b32_e32 v41, v115
	v_mov_b32_e32 v34, v27
	v_mul_f32_e32 v36, v119, v27
	v_pk_fma_f32 v[34:35], v[40:41], v[34:35], v[36:37] op_sel_hi:[1,1,0] neg_lo:[1,0,0] neg_hi:[1,0,0]
	v_mov_b32_e32 v31, v37
	v_mov_b32_e32 v27, v35
.LBB0_640:
	s_or_b64 exec, exec, s[4:5]
	s_waitcnt lgkmcnt(0)
	ds_bpermute_b32 v37, v38, v32
	ds_bpermute_b32 v35, v38, v28
	v_cmp_lt_i32_e32 vcc, 0, v233
	s_and_saveexec_b64 s[4:5], vcc
	s_xor_b64 s[4:5], exec, s[4:5]
	s_cbranch_execz .LBB0_644
	v_cmp_eq_u32_e32 vcc, 1, v233
	s_and_saveexec_b64 s[6:7], vcc
	s_cbranch_execz .LBB0_643
	v_mov_b32_e32 v40, v128
	v_mov_b32_e32 v41, v124
	v_mov_b32_e32 v36, v32
	s_waitcnt lgkmcnt(1)
	v_mul_f32_e32 v32, v124, v37
	v_pk_fma_f32 v[36:37], v[40:41], v[36:37], v[32:33] op_sel_hi:[1,1,0]
	v_mov_b32_e32 v40, v120
	v_mov_b32_e32 v41, v116
	v_mov_b32_e32 v34, v28
	s_waitcnt lgkmcnt(0)
	v_mul_f32_e32 v28, v116, v35
	v_pk_fma_f32 v[34:35], v[40:41], v[34:35], v[28:29] op_sel_hi:[1,1,0]
	v_mov_b32_e32 v32, v36
	v_mov_b32_e32 v28, v34

.LBB0_644:
	s_andn2_saveexec_b64 s[4:5], s[4:5]
	s_cbranch_execz .LBB0_646
	v_mov_b32_e32 v40, v128
	v_mov_b32_e32 v41, v124
	v_mov_b32_e32 v36, v32
	s_waitcnt lgkmcnt(1)
	v_mul_f32_e32 v32, v124, v37
	v_pk_fma_f32 v[36:37], v[40:41], v[36:37], v[32:33] op_sel_hi:[1,1,0] neg_lo:[0,0,1] neg_hi:[0,0,1]
	v_mov_b32_e32 v40, v120
	v_mov_b32_e32 v41, v116
	v_mov_b32_e32 v34, v28
	s_waitcnt lgkmcnt(0)
	v_mul_f32_e32 v28, v116, v35
	v_pk_fma_f32 v[34:35], v[40:41], v[34:35], v[28:29] op_sel_hi:[1,1,0] neg_lo:[0,0,1] neg_hi:[0,0,1]
	v_mov_b32_e32 v32, v36
	v_mov_b32_e32 v28, v34
.LBB0_646:
	s_or_b64 exec, exec, s[4:5]
	s_waitcnt lgkmcnt(0)
	ds_bpermute_b32 v37, v38, v33
	ds_bpermute_b32 v35, v38, v29
	v_cmp_lt_i32_e32 vcc, 0, v233
	s_and_saveexec_b64 s[4:5], vcc
	s_xor_b64 s[4:5], exec, s[4:5]
	s_cbranch_execz .LBB0_650
	v_cmp_eq_u32_e32 vcc, 1, v233
	s_and_saveexec_b64 s[6:7], vcc
	s_cbranch_execz .LBB0_649
	v_mov_b32_e32 v38, v129
	v_mov_b32_e32 v39, v125
	v_mov_b32_e32 v36, v33
	s_waitcnt lgkmcnt(1)
	v_mul_f32_e32 v34, v125, v37
	s_waitcnt lgkmcnt(0)
	v_pk_fma_f32 v[36:37], v[38:39], v[36:37], v[34:35] op_sel_hi:[1,1,0]
	v_mov_b32_e32 v38, v121
	v_mov_b32_e32 v39, v117
	v_mov_b32_e32 v34, v29
	v_mul_f32_e32 v40, v117, v35
	v_pk_fma_f32 v[34:35], v[38:39], v[34:35], v[40:41] op_sel_hi:[1,1,0]
	v_mov_b32_e32 v33, v36
	v_mov_b32_e32 v29, v34

.LBB0_650:
	s_andn2_saveexec_b64 s[4:5], s[4:5]
	s_cbranch_execz .LBB0_652
	v_mov_b32_e32 v38, v129
	v_mov_b32_e32 v39, v125
	v_mov_b32_e32 v36, v33
	s_waitcnt lgkmcnt(1)
	v_mul_f32_e32 v34, v125, v37
	s_waitcnt lgkmcnt(0)
	v_pk_fma_f32 v[36:37], v[38:39], v[36:37], v[34:35] op_sel_hi:[1,1,0] neg_lo:[0,0,1] neg_hi:[0,0,1]
	v_mov_b32_e32 v38, v121
	v_mov_b32_e32 v39, v117
	v_mov_b32_e32 v34, v29
	v_mul_f32_e32 v40, v117, v35
	v_pk_fma_f32 v[34:35], v[38:39], v[34:35], v[40:41] op_sel_hi:[1,1,0] neg_lo:[0,0,1] neg_hi:[0,0,1]
	v_mov_b32_e32 v33, v36
	v_mov_b32_e32 v29, v34

.LBB0_653:
	s_waitcnt lgkmcnt(0)
	v_pk_mul_f32 v[34:35], v[30:31], s[36:37] op_sel_hi:[1,0]
	v_pk_mul_f32 v[38:39], v[26:27], s[36:37] op_sel_hi:[1,0]
	v_pk_mul_f32 v[36:37], v[32:33], s[36:37] op_sel_hi:[1,0]
	v_pk_mul_f32 v[40:41], v[28:29], s[36:37] op_sel_hi:[1,0]
	v_cndmask_b32_e64 v30, v30, v34, s[40:41]
	v_cndmask_b32_e64 v26, v26, v38, s[40:41]
	v_cndmask_b32_e64 v27, v27, v39, s[40:41]
	v_cndmask_b32_e64 v32, v32, v36, s[40:41]
	v_cndmask_b32_e64 v33, v33, v37, s[40:41]
	v_cndmask_b32_e64 v31, v31, v35, s[40:41]
	v_cndmask_b32_e64 v34, v28, v40, s[40:41]
	v_cndmask_b32_e64 v35, v29, v41, s[40:41]
	v_cvt_pk_bf16_f32 v28, v30, v31
	v_cvt_pk_bf16_f32 v29, v32, v33
	v_cvt_pk_bf16_f32 v30, v26, v27
	v_mov_b64_e32 v[26:27], s[62:63]
	s_movk_i32 s4, 0x1200
	v_mad_i64_i32 v[26:27], s[4:5], v190, s4, v[26:27]
	v_lshl_add_u64 v[32:33], v[0:1], 1, v[26:27]
	s_movk_i32 s4, 0xf000
	v_add_co_u32_e32 v32, vcc, s4, v32
	v_mov_b32_e32 v193, v192
	s_nop 0
	v_addc_co_u32_e32 v33, vcc, -1, v33, vcc
	v_cvt_pk_bf16_f32 v31, v34, v35
	flat_store_dwordx4 v[32:33], v[28:31] nt
	v_pk_mul_f32 v[22:23], v[22:23], v[192:193]
	s_and_b64 vcc, exec, s[46:47]
	v_mov_b32_e32 v28, v192
	v_mov_b32_e32 v29, v192
	v_pk_mul_f32 v[24:25], v[24:25], v[28:29]
	v_pk_mul_f32 v[20:21], v[20:21], v[28:29]
	v_pk_mul_f32 v[18:19], v[18:19], v[192:193]
	s_cbranch_vccnz .LBB0_679
	v_and_b32_e32 v29, 64, v226
	v_xor_b32_e32 v28, 16, v226
	v_add_u32_e32 v29, 64, v29
	v_cmp_lt_i32_e32 vcc, v28, v29
	s_nop 1
	v_cndmask_b32_e32 v28, v226, v28, vcc
	v_lshlrev_b32_e32 v32, 2, v28
	ds_bpermute_b32 v31, v32, v22
	ds_bpermute_b32 v29, v32, v18
	v_cmp_lt_i32_e32 vcc, 0, v233
	s_and_saveexec_b64 s[4:5], vcc
	s_xor_b64 s[4:5], exec, s[4:5]
	s_cbranch_execz .LBB0_658
	v_cmp_eq_u32_e32 vcc, 1, v233
	s_and_saveexec_b64 s[6:7], vcc
	s_cbranch_execz .LBB0_657
	v_mov_b32_e32 v34, v22
	v_mov_b32_e32 v35, v122
	v_mov_b32_e32 v30, v126
	s_waitcnt lgkmcnt(0)
	v_pk_mul_f32 v[30:31], v[34:35], v[30:31]
	v_mov_b32_e32 v34, v18
	v_mov_b32_e32 v35, v114
	v_mov_b32_e32 v28, v118
	v_pk_mul_f32 v[28:29], v[34:35], v[28:29]
	v_add_f32_e32 v22, v30, v31
	v_add_f32_e32 v18, v28, v29

.LBB0_658:
	s_andn2_saveexec_b64 s[4:5], s[4:5]
	s_cbranch_execz .LBB0_660
	v_mov_b32_e32 v34, v22
	v_mov_b32_e32 v35, v122
	v_mov_b32_e32 v30, v126
	s_waitcnt lgkmcnt(0)
	v_pk_mul_f32 v[30:31], v[34:35], v[30:31]
	v_mov_b32_e32 v34, v18
	v_mov_b32_e32 v35, v114
	v_mov_b32_e32 v28, v118
	v_pk_mul_f32 v[28:29], v[34:35], v[28:29]
	v_sub_f32_e32 v22, v30, v31
	v_sub_f32_e32 v18, v28, v29
.LBB0_660:
	s_or_b64 exec, exec, s[4:5]
	s_waitcnt lgkmcnt(0)
	ds_bpermute_b32 v31, v32, v23
	ds_bpermute_b32 v29, v32, v19
	v_cmp_lt_i32_e32 vcc, 0, v233
	s_and_saveexec_b64 s[4:5], vcc
	s_xor_b64 s[4:5], exec, s[4:5]
	s_cbranch_execz .LBB0_664
	v_cmp_eq_u32_e32 vcc, 1, v233
	s_and_saveexec_b64 s[6:7], vcc
	s_cbranch_execz .LBB0_663
	v_mov_b32_e32 v122, v127
	v_mov_b32_e32 v30, v23
	v_mul_f32_e32 v28, v127, v23
	s_waitcnt lgkmcnt(0)
	v_pk_fma_f32 v[30:31], v[122:123], v[30:31], v[28:29] op_sel_hi:[1,1,0]
	v_mov_b32_e32 v114, v119
	v_mov_b32_e32 v28, v19
	v_mul_f32_e32 v30, v119, v19
	v_pk_fma_f32 v[28:29], v[114:115], v[28:29], v[30:31] op_sel_hi:[1,1,0]
	v_mov_b32_e32 v23, v31
	v_mov_b32_e32 v19, v29

.LBB0_664:
	s_andn2_saveexec_b64 s[4:5], s[4:5]
	s_cbranch_execz .LBB0_666
	v_mov_b32_e32 v122, v127
	v_mov_b32_e32 v30, v23
	v_mul_f32_e32 v28, v127, v23
	s_waitcnt lgkmcnt(0)
	v_pk_fma_f32 v[30:31], v[122:123], v[30:31], v[28:29] op_sel_hi:[1,1,0] neg_lo:[1,0,0] neg_hi:[1,0,0]
	v_mov_b32_e32 v114, v119
	v_mov_b32_e32 v28, v19
	v_mul_f32_e32 v30, v119, v19
	v_pk_fma_f32 v[28:29], v[114:115], v[28:29], v[30:31] op_sel_hi:[1,1,0] neg_lo:[1,0,0] neg_hi:[1,0,0]
	v_mov_b32_e32 v23, v31
	v_mov_b32_e32 v19, v29
.LBB0_666:
	s_or_b64 exec, exec, s[4:5]
	s_waitcnt lgkmcnt(0)
	ds_bpermute_b32 v31, v32, v24
	ds_bpermute_b32 v29, v32, v20
	v_cmp_lt_i32_e32 vcc, 0, v233
	s_and_saveexec_b64 s[4:5], vcc
	s_xor_b64 s[4:5], exec, s[4:5]
	s_cbranch_execz .LBB0_670
	v_cmp_eq_u32_e32 vcc, 1, v233
	s_and_saveexec_b64 s[6:7], vcc
	s_cbranch_execz .LBB0_669
	v_mov_b32_e32 v34, v128
	v_mov_b32_e32 v35, v124
	v_mov_b32_e32 v30, v24
	s_waitcnt lgkmcnt(1)
	v_mul_f32_e32 v24, v124, v31
	v_pk_fma_f32 v[30:31], v[34:35], v[30:31], v[24:25] op_sel_hi:[1,1,0]
	v_mov_b32_e32 v34, v120
	v_mov_b32_e32 v35, v116
	v_mov_b32_e32 v28, v20
	s_waitcnt lgkmcnt(0)
	v_mul_f32_e32 v20, v116, v29
	v_pk_fma_f32 v[28:29], v[34:35], v[28:29], v[20:21] op_sel_hi:[1,1,0]
	v_mov_b32_e32 v24, v30
	v_mov_b32_e32 v20, v28

.LBB0_670:
	s_andn2_saveexec_b64 s[4:5], s[4:5]
	s_cbranch_execz .LBB0_672
	v_mov_b32_e32 v34, v128
	v_mov_b32_e32 v35, v124
	v_mov_b32_e32 v30, v24
	s_waitcnt lgkmcnt(1)
	v_mul_f32_e32 v24, v124, v31
	v_pk_fma_f32 v[30:31], v[34:35], v[30:31], v[24:25] op_sel_hi:[1,1,0] neg_lo:[0,0,1] neg_hi:[0,0,1]
	v_mov_b32_e32 v34, v120
	v_mov_b32_e32 v35, v116
	v_mov_b32_e32 v28, v20
	s_waitcnt lgkmcnt(0)
	v_mul_f32_e32 v20, v116, v29
	v_pk_fma_f32 v[28:29], v[34:35], v[28:29], v[20:21] op_sel_hi:[1,1,0] neg_lo:[0,0,1] neg_hi:[0,0,1]
	v_mov_b32_e32 v24, v30
	v_mov_b32_e32 v20, v28
.LBB0_672:
	s_or_b64 exec, exec, s[4:5]
	s_waitcnt lgkmcnt(0)
	ds_bpermute_b32 v31, v32, v25
	ds_bpermute_b32 v29, v32, v21
	v_cmp_lt_i32_e32 vcc, 0, v233
	s_and_saveexec_b64 s[4:5], vcc
	s_xor_b64 s[4:5], exec, s[4:5]
	s_cbranch_execz .LBB0_676
	v_cmp_eq_u32_e32 vcc, 1, v233
	s_and_saveexec_b64 s[6:7], vcc
	s_cbranch_execz .LBB0_675
	v_mov_b32_e32 v124, v129
	v_mov_b32_e32 v30, v25
	s_waitcnt lgkmcnt(1)
	v_mul_f32_e32 v28, v125, v31
	s_waitcnt lgkmcnt(0)
	v_pk_fma_f32 v[30:31], v[124:125], v[30:31], v[28:29] op_sel_hi:[1,1,0]
	v_mov_b32_e32 v116, v121
	v_mov_b32_e32 v28, v21
	v_mul_f32_e32 v32, v117, v29
	v_pk_fma_f32 v[28:29], v[116:117], v[28:29], v[32:33] op_sel_hi:[1,1,0]
	v_mov_b32_e32 v25, v30
	v_mov_b32_e32 v21, v28

.LBB0_676:
	s_andn2_saveexec_b64 s[4:5], s[4:5]
	s_cbranch_execz .LBB0_678
	v_mov_b32_e32 v124, v129
	v_mov_b32_e32 v30, v25
	s_waitcnt lgkmcnt(1)
	v_mul_f32_e32 v28, v125, v31
	s_waitcnt lgkmcnt(0)
	v_pk_fma_f32 v[30:31], v[124:125], v[30:31], v[28:29] op_sel_hi:[1,1,0] neg_lo:[0,0,1] neg_hi:[0,0,1]
	v_mov_b32_e32 v116, v121
	v_mov_b32_e32 v28, v21
	v_mul_f32_e32 v32, v117, v29
	v_pk_fma_f32 v[28:29], v[116:117], v[28:29], v[32:33] op_sel_hi:[1,1,0] neg_lo:[0,0,1] neg_hi:[0,0,1]
	v_mov_b32_e32 v25, v30
	v_mov_b32_e32 v21, v28

.LBB0_679:
	s_waitcnt lgkmcnt(0)
	v_pk_mul_f32 v[28:29], v[22:23], s[36:37] op_sel_hi:[1,0]
	v_pk_mul_f32 v[32:33], v[18:19], s[36:37] op_sel_hi:[1,0]
	v_pk_mul_f32 v[34:35], v[20:21], s[36:37] op_sel_hi:[1,0]
	v_cndmask_b32_e64 v22, v22, v28, s[44:45]
	v_cndmask_b32_e64 v23, v23, v29, s[44:45]
	v_cndmask_b32_e64 v28, v20, v34, s[44:45]
	v_cndmask_b32_e64 v20, v18, v32, s[44:45]
	v_cvt_pk_bf16_f32 v18, v22, v23
	v_lshl_add_u64 v[22:23], v[214:215], 1, v[26:27]
	s_movk_i32 s4, 0xf100
	v_add_co_u32_e32 v22, vcc, s4, v22
	v_pk_mul_f32 v[30:31], v[24:25], s[36:37] op_sel_hi:[1,0]
	s_nop 0
	v_addc_co_u32_e32 v23, vcc, -1, v23, vcc
	v_cndmask_b32_e64 v21, v21, v35, s[44:45]
	v_pk_mul_f32 v[16:17], v[16:17], v[176:177] op_sel_hi:[1,0]
	v_pk_mul_f32 v[14:15], v[14:15], v[176:177] op_sel_hi:[1,0]
	v_pk_mul_f32 v[12:13], v[12:13], v[176:177] op_sel_hi:[1,0]
	s_and_b64 vcc, exec, s[42:43]
	v_pk_mul_f32 v[10:11], v[10:11], v[176:177] op_sel_hi:[1,0]
	v_cndmask_b32_e64 v24, v24, v30, s[44:45]
	v_cndmask_b32_e64 v25, v25, v31, s[44:45]
	v_cndmask_b32_e64 v29, v19, v33, s[44:45]
	v_cvt_pk_bf16_f32 v19, v24, v25
	v_cvt_pk_bf16_f32 v20, v20, v29
	v_cvt_pk_bf16_f32 v21, v28, v21
	flat_store_dwordx4 v[22:23], v[18:21] nt
	s_cbranch_vccnz .LBB0_705
	s_nop 0
	v_and_b32_e32 v19, 64, v226
	v_xor_b32_e32 v18, 16, v226
	v_add_u32_e32 v19, 64, v19
	v_cmp_lt_i32_e32 vcc, v18, v19
	s_nop 1
	v_cndmask_b32_e32 v18, v226, v18, vcc
	v_lshlrev_b32_e32 v22, 2, v18
	ds_bpermute_b32 v21, v22, v14
	ds_bpermute_b32 v19, v22, v10
	v_cmp_lt_i32_e32 vcc, 0, v233
	s_and_saveexec_b64 s[4:5], vcc
	s_xor_b64 s[4:5], exec, s[4:5]
	s_cbranch_execz .LBB0_684
	v_cmp_eq_u32_e32 vcc, 1, v233
	s_and_saveexec_b64 s[6:7], vcc
	s_cbranch_execz .LBB0_683
	v_mov_b32_e32 v24, v14
	v_mov_b32_e32 v25, v106
	v_mov_b32_e32 v20, v110
	s_waitcnt lgkmcnt(0)
	v_pk_mul_f32 v[20:21], v[24:25], v[20:21]
	v_mov_b32_e32 v24, v10
	v_mov_b32_e32 v25, v98
	v_mov_b32_e32 v18, v102
	v_pk_mul_f32 v[18:19], v[24:25], v[18:19]
	v_add_f32_e32 v14, v20, v21
	v_add_f32_e32 v10, v18, v19

.LBB0_684:
	s_andn2_saveexec_b64 s[4:5], s[4:5]
	s_cbranch_execz .LBB0_686
	v_mov_b32_e32 v24, v14
	v_mov_b32_e32 v25, v106
	v_mov_b32_e32 v20, v110
	s_waitcnt lgkmcnt(0)
	v_pk_mul_f32 v[20:21], v[24:25], v[20:21]
	v_mov_b32_e32 v24, v10
	v_mov_b32_e32 v25, v98
	v_mov_b32_e32 v18, v102
	v_pk_mul_f32 v[18:19], v[24:25], v[18:19]
	v_sub_f32_e32 v14, v20, v21
	v_sub_f32_e32 v10, v18, v19
.LBB0_686:
	s_or_b64 exec, exec, s[4:5]
	s_waitcnt lgkmcnt(0)
	ds_bpermute_b32 v21, v22, v15
	ds_bpermute_b32 v19, v22, v11
	v_cmp_lt_i32_e32 vcc, 0, v233
	s_and_saveexec_b64 s[4:5], vcc
	s_xor_b64 s[4:5], exec, s[4:5]
	s_cbranch_execz .LBB0_690
	v_cmp_eq_u32_e32 vcc, 1, v233
	s_and_saveexec_b64 s[6:7], vcc
	s_cbranch_execz .LBB0_689
	v_mov_b32_e32 v24, v111
	v_mov_b32_e32 v25, v107
	v_mov_b32_e32 v20, v15
	v_mul_f32_e32 v18, v111, v15
	s_waitcnt lgkmcnt(0)
	v_pk_fma_f32 v[20:21], v[24:25], v[20:21], v[18:19] op_sel_hi:[1,1,0]
	v_mov_b32_e32 v24, v103
	v_mov_b32_e32 v25, v99
	v_mov_b32_e32 v18, v11
	v_mul_f32_e32 v20, v103, v11
	v_pk_fma_f32 v[18:19], v[24:25], v[18:19], v[20:21] op_sel_hi:[1,1,0]
	v_mov_b32_e32 v15, v21
	v_mov_b32_e32 v11, v19

.LBB0_690:
	s_andn2_saveexec_b64 s[4:5], s[4:5]
	s_cbranch_execz .LBB0_692
	v_mov_b32_e32 v24, v111
	v_mov_b32_e32 v25, v107
	v_mov_b32_e32 v20, v15
	v_mul_f32_e32 v18, v111, v15
	s_waitcnt lgkmcnt(0)
	v_pk_fma_f32 v[20:21], v[24:25], v[20:21], v[18:19] op_sel_hi:[1,1,0] neg_lo:[1,0,0] neg_hi:[1,0,0]
	v_mov_b32_e32 v24, v103
	v_mov_b32_e32 v25, v99
	v_mov_b32_e32 v18, v11
	v_mul_f32_e32 v20, v103, v11
	v_pk_fma_f32 v[18:19], v[24:25], v[18:19], v[20:21] op_sel_hi:[1,1,0] neg_lo:[1,0,0] neg_hi:[1,0,0]
	v_mov_b32_e32 v15, v21
	v_mov_b32_e32 v11, v19
.LBB0_692:
	s_or_b64 exec, exec, s[4:5]
	s_waitcnt lgkmcnt(0)
	ds_bpermute_b32 v21, v22, v16
	ds_bpermute_b32 v19, v22, v12
	v_cmp_lt_i32_e32 vcc, 0, v233
	s_and_saveexec_b64 s[4:5], vcc
	s_xor_b64 s[4:5], exec, s[4:5]
	s_cbranch_execz .LBB0_696
	v_cmp_eq_u32_e32 vcc, 1, v233
	s_and_saveexec_b64 s[6:7], vcc
	s_cbranch_execz .LBB0_695
	v_mov_b32_e32 v24, v112
	v_mov_b32_e32 v25, v108
	v_mov_b32_e32 v20, v16
	s_waitcnt lgkmcnt(1)
	v_mul_f32_e32 v16, v108, v21
	v_pk_fma_f32 v[20:21], v[24:25], v[20:21], v[16:17] op_sel_hi:[1,1,0]
	v_mov_b32_e32 v24, v104
	v_mov_b32_e32 v25, v100
	v_mov_b32_e32 v18, v12
	s_waitcnt lgkmcnt(0)
	v_mul_f32_e32 v12, v100, v19
	v_pk_fma_f32 v[18:19], v[24:25], v[18:19], v[12:13] op_sel_hi:[1,1,0]
	v_mov_b32_e32 v16, v20
	v_mov_b32_e32 v12, v18

.LBB0_696:
	s_andn2_saveexec_b64 s[4:5], s[4:5]
	s_cbranch_execz .LBB0_698
	v_mov_b32_e32 v24, v112
	v_mov_b32_e32 v25, v108
	v_mov_b32_e32 v20, v16
	s_waitcnt lgkmcnt(1)
	v_mul_f32_e32 v16, v108, v21
	v_pk_fma_f32 v[20:21], v[24:25], v[20:21], v[16:17] op_sel_hi:[1,1,0] neg_lo:[0,0,1] neg_hi:[0,0,1]
	v_mov_b32_e32 v24, v104
	v_mov_b32_e32 v25, v100
	v_mov_b32_e32 v18, v12
	s_waitcnt lgkmcnt(0)
	v_mul_f32_e32 v12, v100, v19
	v_pk_fma_f32 v[18:19], v[24:25], v[18:19], v[12:13] op_sel_hi:[1,1,0] neg_lo:[0,0,1] neg_hi:[0,0,1]
	v_mov_b32_e32 v16, v20
	v_mov_b32_e32 v12, v18
.LBB0_698:
	s_or_b64 exec, exec, s[4:5]
	s_waitcnt lgkmcnt(0)
	ds_bpermute_b32 v21, v22, v17
	ds_bpermute_b32 v19, v22, v13
	v_cmp_lt_i32_e32 vcc, 0, v233
	s_and_saveexec_b64 s[4:5], vcc
	s_xor_b64 s[4:5], exec, s[4:5]
	s_cbranch_execz .LBB0_702
	v_cmp_eq_u32_e32 vcc, 1, v233
	s_and_saveexec_b64 s[6:7], vcc
	s_cbranch_execz .LBB0_701
	v_mov_b32_e32 v22, v113
	v_mov_b32_e32 v23, v109
	v_mov_b32_e32 v20, v17
	s_waitcnt lgkmcnt(1)
	v_mul_f32_e32 v18, v109, v21
	s_waitcnt lgkmcnt(0)
	v_pk_fma_f32 v[20:21], v[22:23], v[20:21], v[18:19] op_sel_hi:[1,1,0]
	v_mov_b32_e32 v22, v105
	v_mov_b32_e32 v23, v101
	v_mov_b32_e32 v18, v13
	v_mul_f32_e32 v24, v101, v19
	v_pk_fma_f32 v[18:19], v[22:23], v[18:19], v[24:25] op_sel_hi:[1,1,0]
	v_mov_b32_e32 v17, v20
	v_mov_b32_e32 v13, v18

.LBB0_702:
	s_andn2_saveexec_b64 s[4:5], s[4:5]
	s_cbranch_execz .LBB0_704
	v_mov_b32_e32 v22, v113
	v_mov_b32_e32 v23, v109
	v_mov_b32_e32 v20, v17
	s_waitcnt lgkmcnt(1)
	v_mul_f32_e32 v18, v109, v21
	s_waitcnt lgkmcnt(0)
	v_pk_fma_f32 v[20:21], v[22:23], v[20:21], v[18:19] op_sel_hi:[1,1,0] neg_lo:[0,0,1] neg_hi:[0,0,1]
	v_mov_b32_e32 v22, v105
	v_mov_b32_e32 v23, v101
	v_mov_b32_e32 v18, v13
	v_mul_f32_e32 v24, v101, v19
	v_pk_fma_f32 v[18:19], v[22:23], v[18:19], v[24:25] op_sel_hi:[1,1,0] neg_lo:[0,0,1] neg_hi:[0,0,1]
	v_mov_b32_e32 v17, v20
	v_mov_b32_e32 v13, v18

.LBB0_705:
	s_waitcnt lgkmcnt(0)
	v_pk_mul_f32 v[18:19], v[14:15], s[36:37] op_sel_hi:[1,0]
	v_pk_mul_f32 v[22:23], v[10:11], s[36:37] op_sel_hi:[1,0]
	v_pk_mul_f32 v[20:21], v[16:17], s[36:37] op_sel_hi:[1,0]
	v_pk_mul_f32 v[24:25], v[12:13], s[36:37] op_sel_hi:[1,0]
	v_cndmask_b32_e64 v14, v14, v18, s[40:41]
	v_cndmask_b32_e64 v10, v10, v22, s[40:41]
	v_cndmask_b32_e64 v11, v11, v23, s[40:41]
	v_cndmask_b32_e64 v16, v16, v20, s[40:41]
	v_cndmask_b32_e64 v17, v17, v21, s[40:41]
	v_cndmask_b32_e64 v15, v15, v19, s[40:41]
	v_cndmask_b32_e64 v18, v12, v24, s[40:41]
	v_cndmask_b32_e64 v19, v13, v25, s[40:41]
	v_cvt_pk_bf16_f32 v12, v14, v15
	v_cvt_pk_bf16_f32 v13, v16, v17
	v_cvt_pk_bf16_f32 v14, v10, v11
	v_mov_b64_e32 v[10:11], s[62:63]
	s_movk_i32 s4, 0x1200
	v_mad_i64_i32 v[10:11], s[4:5], v174, s4, v[10:11]
	v_lshl_add_u64 v[16:17], v[0:1], 1, v[10:11]
	s_movk_i32 s4, 0xf000
	v_add_co_u32_e32 v16, vcc, s4, v16
	v_mov_b32_e32 v177, v176
	s_nop 0
	v_addc_co_u32_e32 v17, vcc, -1, v17, vcc
	v_cvt_pk_bf16_f32 v15, v18, v19
	flat_store_dwordx4 v[16:17], v[12:15] nt
	v_pk_mul_f32 v[6:7], v[6:7], v[176:177]
	s_and_b64 vcc, exec, s[46:47]
	v_mov_b32_e32 v12, v176
	v_mov_b32_e32 v13, v176
	v_pk_mul_f32 v[8:9], v[8:9], v[12:13]
	v_pk_mul_f32 v[4:5], v[4:5], v[12:13]
	v_pk_mul_f32 v[2:3], v[2:3], v[176:177]
	s_cbranch_vccnz .LBB0_731
	v_and_b32_e32 v12, 64, v226
	v_xor_b32_e32 v0, 16, v226
	v_add_u32_e32 v12, 64, v12
	v_cmp_lt_i32_e32 vcc, v0, v12
	s_nop 1
	v_cndmask_b32_e32 v0, v226, v0, vcc
	v_lshlrev_b32_e32 v0, 2, v0
	ds_bpermute_b32 v15, v0, v6
	ds_bpermute_b32 v13, v0, v2
	v_cmp_lt_i32_e32 vcc, 0, v233
	s_and_saveexec_b64 s[4:5], vcc
	s_xor_b64 s[4:5], exec, s[4:5]
	s_cbranch_execz .LBB0_710
	v_cmp_eq_u32_e32 vcc, 1, v233
	s_and_saveexec_b64 s[6:7], vcc
	s_cbranch_execz .LBB0_709
	v_mov_b32_e32 v16, v6
	v_mov_b32_e32 v17, v106
	v_mov_b32_e32 v14, v110
	s_waitcnt lgkmcnt(0)
	v_pk_mul_f32 v[14:15], v[16:17], v[14:15]
	v_mov_b32_e32 v16, v2
	v_mov_b32_e32 v17, v98
	v_mov_b32_e32 v12, v102
	v_pk_mul_f32 v[12:13], v[16:17], v[12:13]
	v_add_f32_e32 v6, v14, v15
	v_add_f32_e32 v2, v12, v13

.LBB0_710:
	s_andn2_saveexec_b64 s[4:5], s[4:5]
	s_cbranch_execz .LBB0_712
	v_mov_b32_e32 v16, v6
	v_mov_b32_e32 v17, v106
	v_mov_b32_e32 v14, v110
	s_waitcnt lgkmcnt(0)
	v_pk_mul_f32 v[14:15], v[16:17], v[14:15]
	v_mov_b32_e32 v16, v2
	v_mov_b32_e32 v17, v98
	v_mov_b32_e32 v12, v102
	v_pk_mul_f32 v[12:13], v[16:17], v[12:13]
	v_sub_f32_e32 v6, v14, v15
	v_sub_f32_e32 v2, v12, v13
.LBB0_712:
	s_or_b64 exec, exec, s[4:5]
	s_waitcnt lgkmcnt(0)
	ds_bpermute_b32 v15, v0, v7
	ds_bpermute_b32 v13, v0, v3
	v_cmp_lt_i32_e32 vcc, 0, v233
	s_and_saveexec_b64 s[4:5], vcc
	s_xor_b64 s[4:5], exec, s[4:5]
	s_cbranch_execz .LBB0_716
	v_cmp_eq_u32_e32 vcc, 1, v233
	s_and_saveexec_b64 s[6:7], vcc
	s_cbranch_execz .LBB0_715
	v_mov_b32_e32 v106, v111
	v_mov_b32_e32 v14, v7
	v_mul_f32_e32 v12, v111, v7
	s_waitcnt lgkmcnt(0)
	v_pk_fma_f32 v[14:15], v[106:107], v[14:15], v[12:13] op_sel_hi:[1,1,0]
	v_mov_b32_e32 v98, v103
	v_mov_b32_e32 v12, v3
	v_mul_f32_e32 v14, v103, v3
	v_pk_fma_f32 v[12:13], v[98:99], v[12:13], v[14:15] op_sel_hi:[1,1,0]
	v_mov_b32_e32 v7, v15
	v_mov_b32_e32 v3, v13

.LBB0_716:
	s_andn2_saveexec_b64 s[4:5], s[4:5]
	s_cbranch_execz .LBB0_718
	v_mov_b32_e32 v106, v111
	v_mov_b32_e32 v14, v7
	v_mul_f32_e32 v12, v111, v7
	s_waitcnt lgkmcnt(0)
	v_pk_fma_f32 v[14:15], v[106:107], v[14:15], v[12:13] op_sel_hi:[1,1,0] neg_lo:[1,0,0] neg_hi:[1,0,0]
	v_mov_b32_e32 v98, v103
	v_mov_b32_e32 v12, v3
	v_mul_f32_e32 v14, v103, v3
	v_pk_fma_f32 v[12:13], v[98:99], v[12:13], v[14:15] op_sel_hi:[1,1,0] neg_lo:[1,0,0] neg_hi:[1,0,0]
	v_mov_b32_e32 v7, v15
	v_mov_b32_e32 v3, v13
.LBB0_718:
	s_or_b64 exec, exec, s[4:5]
	s_waitcnt lgkmcnt(0)
	ds_bpermute_b32 v15, v0, v8
	ds_bpermute_b32 v13, v0, v4
	v_cmp_lt_i32_e32 vcc, 0, v233
	s_and_saveexec_b64 s[4:5], vcc
	s_xor_b64 s[4:5], exec, s[4:5]
	s_cbranch_execz .LBB0_722
	v_cmp_eq_u32_e32 vcc, 1, v233
	s_and_saveexec_b64 s[6:7], vcc
	s_cbranch_execz .LBB0_721
	v_mov_b32_e32 v16, v112
	v_mov_b32_e32 v17, v108
	v_mov_b32_e32 v14, v8
	s_waitcnt lgkmcnt(1)
	v_mul_f32_e32 v8, v108, v15
	v_pk_fma_f32 v[14:15], v[16:17], v[14:15], v[8:9] op_sel_hi:[1,1,0]
	v_mov_b32_e32 v16, v104
	v_mov_b32_e32 v17, v100
	v_mov_b32_e32 v12, v4
	s_waitcnt lgkmcnt(0)
	v_mul_f32_e32 v4, v100, v13
	v_pk_fma_f32 v[12:13], v[16:17], v[12:13], v[4:5] op_sel_hi:[1,1,0]
	v_mov_b32_e32 v8, v14
	v_mov_b32_e32 v4, v12

.LBB0_722:
	s_andn2_saveexec_b64 s[4:5], s[4:5]
	s_cbranch_execz .LBB0_724
	v_mov_b32_e32 v16, v112
	v_mov_b32_e32 v17, v108
	v_mov_b32_e32 v14, v8
	s_waitcnt lgkmcnt(1)
	v_mul_f32_e32 v8, v108, v15
	v_pk_fma_f32 v[14:15], v[16:17], v[14:15], v[8:9] op_sel_hi:[1,1,0] neg_lo:[0,0,1] neg_hi:[0,0,1]
	v_mov_b32_e32 v16, v104
	v_mov_b32_e32 v17, v100
	v_mov_b32_e32 v12, v4
	s_waitcnt lgkmcnt(0)
	v_mul_f32_e32 v4, v100, v13
	v_pk_fma_f32 v[12:13], v[16:17], v[12:13], v[4:5] op_sel_hi:[1,1,0] neg_lo:[0,0,1] neg_hi:[0,0,1]
	v_mov_b32_e32 v8, v14
	v_mov_b32_e32 v4, v12
.LBB0_724:
	s_or_b64 exec, exec, s[4:5]
	s_waitcnt lgkmcnt(0)
	ds_bpermute_b32 v15, v0, v9
	ds_bpermute_b32 v13, v0, v5
	v_cmp_lt_i32_e32 vcc, 0, v233
	s_and_saveexec_b64 s[4:5], vcc
	s_xor_b64 s[4:5], exec, s[4:5]
	s_cbranch_execz .LBB0_728
	v_cmp_eq_u32_e32 vcc, 1, v233
	s_and_saveexec_b64 s[6:7], vcc
	s_cbranch_execz .LBB0_727
	v_mov_b32_e32 v108, v113
	v_mov_b32_e32 v14, v9
	s_waitcnt lgkmcnt(1)
	v_mul_f32_e32 v0, v109, v15
	v_pk_fma_f32 v[14:15], v[108:109], v[14:15], v[0:1] op_sel_hi:[1,1,0]
	v_mov_b32_e32 v100, v105
	v_mov_b32_e32 v12, v5
	s_waitcnt lgkmcnt(0)
	v_mul_f32_e32 v0, v101, v13
	v_pk_fma_f32 v[12:13], v[100:101], v[12:13], v[0:1] op_sel_hi:[1,1,0]
	v_mov_b32_e32 v9, v14
	v_mov_b32_e32 v5, v12

.LBB0_728:
	s_andn2_saveexec_b64 s[4:5], s[4:5]
	s_cbranch_execz .LBB0_730
	v_mov_b32_e32 v108, v113
	v_mov_b32_e32 v14, v9
	s_waitcnt lgkmcnt(1)
	v_mul_f32_e32 v0, v109, v15
	v_pk_fma_f32 v[14:15], v[108:109], v[14:15], v[0:1] op_sel_hi:[1,1,0] neg_lo:[0,0,1] neg_hi:[0,0,1]
	v_mov_b32_e32 v100, v105
	v_mov_b32_e32 v12, v5
	s_waitcnt lgkmcnt(0)
	v_mul_f32_e32 v0, v101, v13
	v_pk_fma_f32 v[12:13], v[100:101], v[12:13], v[0:1] op_sel_hi:[1,1,0] neg_lo:[0,0,1] neg_hi:[0,0,1]
	v_mov_b32_e32 v9, v14
	v_mov_b32_e32 v5, v12

.LBB0_734:
	v_readlane_b32 s80, v255, 12
	s_mov_b32 s84, s80
	s_mov_b32 s80, s28
	s_barrier
	v_readlane_b32 s81, v255, 13
